# non-temporal (nt) cache policy on the P3 scan's streaming state loads and stores
# speedup vs baseline: 1.0044x; 1.0044x over previous
; DI void scan_item(const Ctx& c, int st, int slice, int lane) {
;     ...
;     for (int i0 = 0; i0 < nch; i0 += 8) {
;         u32x4 ld[8]; float bt[8], ml[8];
; #pragma unroll
;         for (int u = 0; u < 8; ++u) { const int ch = d ? chunk0 + nch - 1 - (i0 + u) : chunk0 + i0 + u; const size_t ti = (size_t)(d * NCHUNK + ch) * 4 + head;
;             ld[u] = act ? *(const u32x4*)(CST + ti * ST_ELEMS + e0) : (u32x4){0u, 0u, 0u, 0u}; bt[u] = CHSC[ti * 2]; ml[u] = CHSC[ti * 2 + 1]; }
.LBB0_322:
	s_add_i32 s42, s51, s55
	s_and_b64 s[12:13], s[10:11], exec
	s_cselect_b32 s12, s42, s54
	s_add_i32 s12, s12, s52
	s_ashr_i32 s13, s12, 31
	s_lshl_b64 s[12:13], s[12:13], 2
	s_or_b64 s[40:41], s[12:13], s[8:9]
	s_mul_i32 s65, s41, 0x8100
	v_mov_b32_e32 v28, 0
	v_mov_b32_e32 v29, 0
	v_mov_b32_e32 v30, 0
	v_mov_b32_e32 v31, 0
	s_and_saveexec_b64 s[12:13], vcc
	s_cbranch_execz .LBB0_324
	v_mad_u64_u32 v[0:1], s[14:15], s40, v59, v[32:33]
	v_add_u32_e32 v1, s65, v1
	global_load_dwordx4 v[28:31], v[0:1], off nt
.LBB0_324:
	s_or_b64 exec, exec, s[12:13]
	s_lshl_b64 s[12:13], s[40:41], 3
	s_add_u32 s12, s33, s12
	s_addc_u32 s13, s44, s13
	v_mov_b32_e32 v16, 0
	global_load_dwordx2 v[56:57], v16, s[12:13]
	s_xor_b32 s12, s55, -2
	s_add_i32 s14, s12, s53
	s_add_i32 s15, s42, 1
	s_and_b64 s[12:13], s[10:11], exec
	s_cselect_b32 s12, s15, s14
	s_add_i32 s12, s12, s52
	s_ashr_i32 s13, s12, 31
	s_lshl_b64 s[12:13], s[12:13], 2
	s_or_b64 s[34:35], s[12:13], s[8:9]
	s_mul_i32 s64, s35, 0x8100
	v_mov_b32_e32 v24, 0
	v_mov_b32_e32 v25, 0
	v_mov_b32_e32 v26, 0
	v_mov_b32_e32 v27, 0
	s_and_saveexec_b64 s[12:13], vcc
	s_cbranch_execz .LBB0_326
	v_mad_u64_u32 v[0:1], s[14:15], s34, v59, v[32:33]
	v_add_u32_e32 v1, s64, v1
	global_load_dwordx4 v[24:27], v[0:1], off nt
.LBB0_326:
	s_or_b64 exec, exec, s[12:13]
	s_lshl_b64 s[12:13], s[34:35], 3
	s_add_u32 s12, s33, s12
	s_addc_u32 s13, s44, s13
	global_load_dwordx2 v[54:55], v16, s[12:13]
	s_xor_b32 s12, s55, -3
	s_add_i32 s14, s12, s53
	s_add_i32 s15, s42, 2
	s_and_b64 s[12:13], s[10:11], exec
	s_cselect_b32 s12, s15, s14
	s_add_i32 s12, s12, s52
	s_ashr_i32 s13, s12, 31
	s_lshl_b64 s[12:13], s[12:13], 2
	s_or_b64 s[30:31], s[12:13], s[8:9]
	s_mul_i32 s63, s31, 0x8100
	v_mov_b32_e32 v17, 0
	v_mov_b32_e32 v18, 0
	v_mov_b32_e32 v19, 0
	s_and_saveexec_b64 s[12:13], vcc
	s_cbranch_execz .LBB0_328
	v_mad_u64_u32 v[0:1], s[14:15], s30, v59, v[32:33]
	v_add_u32_e32 v1, s63, v1
	global_load_dwordx4 v[16:19], v[0:1], off nt
.LBB0_328:
	s_or_b64 exec, exec, s[12:13]
	s_lshl_b64 s[12:13], s[30:31], 3
	s_add_u32 s12, s33, s12
	s_addc_u32 s13, s44, s13
	v_mov_b32_e32 v8, 0
	global_load_dwordx2 v[52:53], v8, s[12:13]
	s_xor_b32 s12, s55, -4
	s_add_i32 s14, s12, s53
	s_add_i32 s15, s42, 3
	s_and_b64 s[12:13], s[10:11], exec
	s_cselect_b32 s12, s15, s14
	s_add_i32 s12, s12, s52
	s_ashr_i32 s13, s12, 31
	s_lshl_b64 s[12:13], s[12:13], 2
	s_or_b64 s[20:21], s[12:13], s[8:9]
	s_mul_i32 s62, s21, 0x8100
	v_mov_b32_e32 v20, 0
	v_mov_b32_e32 v21, 0
	v_mov_b32_e32 v22, 0
	v_mov_b32_e32 v23, 0
	s_and_saveexec_b64 s[12:13], vcc
	s_cbranch_execz .LBB0_330
	v_mad_u64_u32 v[0:1], s[14:15], s20, v59, v[32:33]
	v_add_u32_e32 v1, s62, v1
	global_load_dwordx4 v[20:23], v[0:1], off nt
.LBB0_330:
	s_or_b64 exec, exec, s[12:13]
	s_lshl_b64 s[12:13], s[20:21], 3
	s_add_u32 s12, s33, s12
	s_addc_u32 s13, s44, s13
	global_load_dwordx2 v[50:51], v8, s[12:13]
	s_xor_b32 s12, s55, -5
	s_add_i32 s14, s12, s53
	s_add_i32 s15, s42, 4
	s_and_b64 s[12:13], s[10:11], exec
	s_cselect_b32 s12, s15, s14
	s_add_i32 s12, s12, s52
	s_ashr_i32 s13, s12, 31
	s_lshl_b64 s[12:13], s[12:13], 2
	s_or_b64 s[18:19], s[12:13], s[8:9]
	s_mul_i32 s61, s19, 0x8100
	v_mov_b32_e32 v9, 0
	v_mov_b32_e32 v10, 0
	v_mov_b32_e32 v11, 0
	s_and_saveexec_b64 s[12:13], vcc
	s_cbranch_execz .LBB0_332
	v_mad_u64_u32 v[0:1], s[14:15], s18, v59, v[32:33]
	v_add_u32_e32 v1, s61, v1
	global_load_dwordx4 v[8:11], v[0:1], off nt
.LBB0_332:
	s_or_b64 exec, exec, s[12:13]
	s_lshl_b64 s[12:13], s[18:19], 3
	s_add_u32 s12, s33, s12
	s_addc_u32 s13, s44, s13
	v_mov_b32_e32 v0, 0
	global_load_dwordx2 v[48:49], v0, s[12:13]
	s_xor_b32 s12, s55, -6
	s_add_i32 s14, s12, s53
	s_add_i32 s15, s42, 5
	s_and_b64 s[12:13], s[10:11], exec
	s_cselect_b32 s12, s15, s14
	s_add_i32 s12, s12, s52
	s_ashr_i32 s13, s12, 31
	s_lshl_b64 s[12:13], s[12:13], 2
	s_or_b64 s[16:17], s[12:13], s[8:9]
	s_mul_i32 s60, s17, 0x8100
	v_mov_b32_e32 v12, 0
	v_mov_b32_e32 v13, 0
	v_mov_b32_e32 v14, 0
	v_mov_b32_e32 v15, 0
	s_and_saveexec_b64 s[12:13], vcc
	s_cbranch_execz .LBB0_334
	v_mad_u64_u32 v[2:3], s[14:15], s16, v59, v[32:33]
	v_add_u32_e32 v3, s60, v3
	global_load_dwordx4 v[12:15], v[2:3], off nt
.LBB0_334:
	s_or_b64 exec, exec, s[12:13]
	s_lshl_b64 s[12:13], s[16:17], 3
	s_add_u32 s12, s33, s12
	s_addc_u32 s13, s44, s13
	global_load_dwordx2 v[46:47], v0, s[12:13]
	s_xor_b32 s12, s55, -7
	s_add_i32 s14, s12, s53
	s_add_i32 s15, s42, 6
	s_and_b64 s[12:13], s[10:11], exec
	s_cselect_b32 s12, s15, s14
	s_add_i32 s12, s12, s52
	s_ashr_i32 s13, s12, 31
	s_lshl_b64 s[12:13], s[12:13], 2
	s_or_b64 s[14:15], s[12:13], s[8:9]
	s_mul_i32 s59, s15, 0x8100
	v_mov_b32_e32 v1, 0
	v_mov_b32_e32 v2, 0
	v_mov_b32_e32 v3, 0
	s_and_saveexec_b64 s[12:13], vcc
	s_cbranch_execz .LBB0_336
	v_mad_u64_u32 v[0:1], s[66:67], s14, v59, v[32:33]
	v_add_u32_e32 v1, s59, v1
	global_load_dwordx4 v[0:3], v[0:1], off nt
.LBB0_336:
	s_or_b64 exec, exec, s[12:13]
	s_lshl_b64 s[12:13], s[14:15], 3
	s_add_u32 s12, s33, s12
	s_addc_u32 s13, s44, s13
	v_mov_b32_e32 v4, 0
	global_load_dwordx2 v[36:37], v4, s[12:13]
	s_xor_b32 s12, s55, -8
	s_add_i32 s43, s12, s53
	s_add_i32 s42, s42, 7
	s_and_b64 s[12:13], s[10:11], exec
	s_cselect_b32 s12, s42, s43
	s_add_i32 s12, s12, s52
	s_ashr_i32 s13, s12, 31
	s_lshl_b64 s[12:13], s[12:13], 2
	s_or_b64 s[12:13], s[12:13], s[8:9]
	s_mul_i32 s58, s13, 0x8100
	v_mov_b32_e32 v5, 0
	v_mov_b32_e32 v6, 0
	v_mov_b32_e32 v7, 0
	s_and_saveexec_b64 s[42:43], vcc
	s_cbranch_execz .LBB0_338
	v_mad_u64_u32 v[4:5], s[66:67], s12, v59, v[32:33]
	v_add_u32_e32 v5, s58, v5
	global_load_dwordx4 v[4:7], v[4:5], off nt

; DI unsigned pk2(float lo, float hi) { const f32n2 v = {lo, hi}; return __builtin_bit_cast(unsigned, __builtin_convertvector(v, bf16n2)); }
; DI void scan_item(const Ctx& c, int st, int slice, int lane) {
;     ...
;         for (int u = 0; u < 8; ++u) { const int ch = d ? chunk0 + nch - 1 - (i0 + u) : chunk0 + i0 + u; const size_t ti = (size_t)(d * NCHUNK + ch) * 4 + head;
;             if (slice == 0 && lane == 0) MP[ti] = m;
;             u32x4 o; o.x = pk2(C[0], C[1]); o.y = pk2(C[2], C[3]); o.z = pk2(C[4], C[5]); o.w = pk2(C[6], C[7]);
;             if (act) *(u32x4*)(CST + ti * ST_ELEMS + e0) = o;
.LBB0_340:
	s_or_b64 exec, exec, s[42:43]
	s_and_saveexec_b64 s[42:43], s[0:1]
	s_xor_b64 s[42:43], exec, s[42:43]
	s_andn2_saveexec_b64 s[42:43], s[42:43]
	s_cbranch_execz .LBB0_342
	v_mad_u64_u32 v[66:67], s[40:41], s40, v59, v[32:33]
	v_cvt_pk_bf16_f32 v65, v44, v45
	v_cvt_pk_bf16_f32 v64, v42, v43
	v_cvt_pk_bf16_f32 v63, v40, v41
	v_cvt_pk_bf16_f32 v62, v38, v39
	v_add_u32_e32 v67, s65, v67
	global_store_dwordx4 v[66:67], v[62:65], off nt

; DI unsigned pk2(float lo, float hi) { const f32n2 v = {lo, hi}; return __builtin_bit_cast(unsigned, __builtin_convertvector(v, bf16n2)); }
; DI float bflo(unsigned w) { return __uint_as_float(w << 16); }
; DI float bfhi(unsigned w) { return __uint_as_float(w & 0xffff0000u); }
; DI void scan_item(const Ctx& c, int st, int slice, int lane) {
;     ...
;         for (int u = 0; u < 8; ++u) { const int ch = d ? chunk0 + nch - 1 - (i0 + u) : chunk0 + i0 + u; const size_t ti = (size_t)(d * NCHUNK + ch) * 4 + head;
;             if (slice == 0 && lane == 0) MP[ti] = m;
;             u32x4 o; o.x = pk2(C[0], C[1]); o.y = pk2(C[2], C[3]); o.z = pk2(C[4], C[5]); o.w = pk2(C[6], C[7]);
;             if (act) *(u32x4*)(CST + ti * ST_ELEMS + e0) = o;
;             const float mn = fmaxf(bt[u] + m, ml[u]), sp = __expf(bt[u] + m - mn), sl = __expf(ml[u] - mn); m = mn;
; #pragma unroll
;             for (int e = 0; e < 8; ++e) { const unsigned w = ld[u][e >> 1]; const float cl = (e & 1) ? bfhi(w) : bflo(w); C[e] = sp * C[e] + sl * cl; } }
.LBB0_344:
	s_or_b64 exec, exec, s[40:41]
	v_sub_f32_e32 v57, v57, v56
	v_sub_f32_e32 v61, v61, v56
	v_mul_f32_e32 v57, 0x3fb8aa3b, v57
	v_mul_f32_e32 v61, 0x3fb8aa3b, v61
	v_exp_f32_e32 v62, v57
	v_exp_f32_e32 v64, v61
	v_lshlrev_b32_e32 v66, 16, v28
	v_and_b32_e32 v67, 0xffff0000, v28
	v_lshlrev_b32_e32 v28, 16, v29
	v_and_b32_e32 v29, 0xffff0000, v29
	v_pk_mul_f32 v[28:29], v[62:63], v[28:29] op_sel_hi:[0,1]
	v_pk_fma_f32 v[28:29], v[40:41], v[64:65], v[28:29] op_sel_hi:[1,0,1]
	v_lshlrev_b32_e32 v40, 16, v30
	v_and_b32_e32 v41, 0xffff0000, v30
	v_lshlrev_b32_e32 v30, 16, v31
	v_and_b32_e32 v31, 0xffff0000, v31
	v_pk_mul_f32 v[66:67], v[62:63], v[66:67] op_sel_hi:[0,1]
	v_pk_mul_f32 v[40:41], v[62:63], v[40:41] op_sel_hi:[0,1]
	v_pk_mul_f32 v[30:31], v[62:63], v[30:31] op_sel_hi:[0,1]
	v_pk_fma_f32 v[38:39], v[38:39], v[64:65], v[66:67] op_sel_hi:[1,0,1]
	v_pk_fma_f32 v[40:41], v[42:43], v[64:65], v[40:41] op_sel_hi:[1,0,1]
	v_pk_fma_f32 v[30:31], v[44:45], v[64:65], v[30:31] op_sel_hi:[1,0,1]
	s_and_saveexec_b64 s[40:41], vcc
	s_cbranch_execz .LBB0_346
	v_mad_u64_u32 v[62:63], s[34:35], s34, v59, v[32:33]
	v_cvt_pk_bf16_f32 v45, v30, v31
	v_cvt_pk_bf16_f32 v44, v40, v41
	v_cvt_pk_bf16_f32 v43, v28, v29
	v_cvt_pk_bf16_f32 v42, v38, v39
	v_add_u32_e32 v63, s64, v63
	global_store_dwordx4 v[62:63], v[42:45], off nt

; DI unsigned pk2(float lo, float hi) { const f32n2 v = {lo, hi}; return __builtin_bit_cast(unsigned, __builtin_convertvector(v, bf16n2)); }
; DI float bflo(unsigned w) { return __uint_as_float(w << 16); }
; DI float bfhi(unsigned w) { return __uint_as_float(w & 0xffff0000u); }
; DI void scan_item(const Ctx& c, int st, int slice, int lane) {
;     ...
;         for (int u = 0; u < 8; ++u) { const int ch = d ? chunk0 + nch - 1 - (i0 + u) : chunk0 + i0 + u; const size_t ti = (size_t)(d * NCHUNK + ch) * 4 + head;
;             if (slice == 0 && lane == 0) MP[ti] = m;
;             u32x4 o; o.x = pk2(C[0], C[1]); o.y = pk2(C[2], C[3]); o.z = pk2(C[4], C[5]); o.w = pk2(C[6], C[7]);
;             if (act) *(u32x4*)(CST + ti * ST_ELEMS + e0) = o;
;             const float mn = fmaxf(bt[u] + m, ml[u]), sp = __expf(bt[u] + m - mn), sl = __expf(ml[u] - mn); m = mn;
; #pragma unroll
;             for (int e = 0; e < 8; ++e) { const unsigned w = ld[u][e >> 1]; const float cl = (e & 1) ? bfhi(w) : bflo(w); C[e] = sp * C[e] + sl * cl; } }
.LBB0_348:
	s_or_b64 exec, exec, s[34:35]
	v_sub_f32_e32 v44, v55, v42
	v_sub_f32_e32 v43, v43, v42
	v_mul_f32_e32 v44, 0x3fb8aa3b, v44
	v_mul_f32_e32 v43, 0x3fb8aa3b, v43
	v_exp_f32_e32 v44, v44
	v_exp_f32_e32 v54, v43
	v_lshlrev_b32_e32 v56, 16, v24
	v_and_b32_e32 v57, 0xffff0000, v24
	v_lshlrev_b32_e32 v24, 16, v25
	v_and_b32_e32 v25, 0xffff0000, v25
	v_pk_mul_f32 v[24:25], v[44:45], v[24:25] op_sel_hi:[0,1]
	v_pk_fma_f32 v[24:25], v[28:29], v[54:55], v[24:25] op_sel_hi:[1,0,1]
	v_lshlrev_b32_e32 v28, 16, v26
	v_and_b32_e32 v29, 0xffff0000, v26
	v_lshlrev_b32_e32 v26, 16, v27
	v_and_b32_e32 v27, 0xffff0000, v27
	v_pk_mul_f32 v[56:57], v[44:45], v[56:57] op_sel_hi:[0,1]
	v_pk_mul_f32 v[28:29], v[44:45], v[28:29] op_sel_hi:[0,1]
	v_pk_mul_f32 v[26:27], v[44:45], v[26:27] op_sel_hi:[0,1]
	v_pk_fma_f32 v[38:39], v[38:39], v[54:55], v[56:57] op_sel_hi:[1,0,1]
	v_pk_fma_f32 v[28:29], v[40:41], v[54:55], v[28:29] op_sel_hi:[1,0,1]
	v_pk_fma_f32 v[26:27], v[30:31], v[54:55], v[26:27] op_sel_hi:[1,0,1]
	s_and_saveexec_b64 s[34:35], vcc
	s_cbranch_execz .LBB0_350
	v_mad_u64_u32 v[30:31], s[30:31], s30, v59, v[32:33]
	v_cvt_pk_bf16_f32 v57, v26, v27
	v_cvt_pk_bf16_f32 v56, v28, v29
	v_cvt_pk_bf16_f32 v55, v24, v25
	v_cvt_pk_bf16_f32 v54, v38, v39
	v_add_u32_e32 v31, s63, v31
	global_store_dwordx4 v[30:31], v[54:57], off nt

; DI unsigned pk2(float lo, float hi) { const f32n2 v = {lo, hi}; return __builtin_bit_cast(unsigned, __builtin_convertvector(v, bf16n2)); }
; DI float bflo(unsigned w) { return __uint_as_float(w << 16); }
; DI float bfhi(unsigned w) { return __uint_as_float(w & 0xffff0000u); }
; DI void scan_item(const Ctx& c, int st, int slice, int lane) {
;     ...
;         for (int u = 0; u < 8; ++u) { const int ch = d ? chunk0 + nch - 1 - (i0 + u) : chunk0 + i0 + u; const size_t ti = (size_t)(d * NCHUNK + ch) * 4 + head;
;             if (slice == 0 && lane == 0) MP[ti] = m;
;             u32x4 o; o.x = pk2(C[0], C[1]); o.y = pk2(C[2], C[3]); o.z = pk2(C[4], C[5]); o.w = pk2(C[6], C[7]);
;             if (act) *(u32x4*)(CST + ti * ST_ELEMS + e0) = o;
;             const float mn = fmaxf(bt[u] + m, ml[u]), sp = __expf(bt[u] + m - mn), sl = __expf(ml[u] - mn); m = mn;
; #pragma unroll
;             for (int e = 0; e < 8; ++e) { const unsigned w = ld[u][e >> 1]; const float cl = (e & 1) ? bfhi(w) : bflo(w); C[e] = sp * C[e] + sl * cl; } }
.LBB0_352:
	s_or_b64 exec, exec, s[30:31]
	v_sub_f32_e32 v31, v53, v40
	v_sub_f32_e32 v30, v30, v40
	v_mul_f32_e32 v31, 0x3fb8aa3b, v31
	v_mul_f32_e32 v30, 0x3fb8aa3b, v30
	v_exp_f32_e32 v42, v31
	v_exp_f32_e32 v44, v30
	v_lshlrev_b32_e32 v30, 16, v16
	v_and_b32_e32 v31, 0xffff0000, v16
	v_lshlrev_b32_e32 v16, 16, v17
	v_and_b32_e32 v17, 0xffff0000, v17
	v_pk_mul_f32 v[16:17], v[42:43], v[16:17] op_sel_hi:[0,1]
	v_pk_fma_f32 v[16:17], v[24:25], v[44:45], v[16:17] op_sel_hi:[1,0,1]
	v_lshlrev_b32_e32 v24, 16, v18
	v_and_b32_e32 v25, 0xffff0000, v18
	v_lshlrev_b32_e32 v18, 16, v19
	v_and_b32_e32 v19, 0xffff0000, v19
	v_pk_mul_f32 v[30:31], v[42:43], v[30:31] op_sel_hi:[0,1]
	v_pk_mul_f32 v[24:25], v[42:43], v[24:25] op_sel_hi:[0,1]
	v_pk_mul_f32 v[18:19], v[42:43], v[18:19] op_sel_hi:[0,1]
	v_pk_fma_f32 v[30:31], v[38:39], v[44:45], v[30:31] op_sel_hi:[1,0,1]
	v_pk_fma_f32 v[24:25], v[28:29], v[44:45], v[24:25] op_sel_hi:[1,0,1]
	v_pk_fma_f32 v[18:19], v[26:27], v[44:45], v[18:19] op_sel_hi:[1,0,1]
	s_and_saveexec_b64 s[30:31], vcc
	s_cbranch_execz .LBB0_354
	v_mad_u64_u32 v[38:39], s[20:21], s20, v59, v[32:33]
	v_cvt_pk_bf16_f32 v29, v18, v19
	v_cvt_pk_bf16_f32 v28, v24, v25
	v_cvt_pk_bf16_f32 v27, v16, v17
	v_cvt_pk_bf16_f32 v26, v30, v31
	v_add_u32_e32 v39, s62, v39
	global_store_dwordx4 v[38:39], v[26:29], off nt

; DI unsigned pk2(float lo, float hi) { const f32n2 v = {lo, hi}; return __builtin_bit_cast(unsigned, __builtin_convertvector(v, bf16n2)); }
; DI float bflo(unsigned w) { return __uint_as_float(w << 16); }
; DI float bfhi(unsigned w) { return __uint_as_float(w & 0xffff0000u); }
; DI void scan_item(const Ctx& c, int st, int slice, int lane) {
;     ...
;         for (int u = 0; u < 8; ++u) { const int ch = d ? chunk0 + nch - 1 - (i0 + u) : chunk0 + i0 + u; const size_t ti = (size_t)(d * NCHUNK + ch) * 4 + head;
;             if (slice == 0 && lane == 0) MP[ti] = m;
;             u32x4 o; o.x = pk2(C[0], C[1]); o.y = pk2(C[2], C[3]); o.z = pk2(C[4], C[5]); o.w = pk2(C[6], C[7]);
;             if (act) *(u32x4*)(CST + ti * ST_ELEMS + e0) = o;
;             const float mn = fmaxf(bt[u] + m, ml[u]), sp = __expf(bt[u] + m - mn), sl = __expf(ml[u] - mn); m = mn;
; #pragma unroll
;             for (int e = 0; e < 8; ++e) { const unsigned w = ld[u][e >> 1]; const float cl = (e & 1) ? bfhi(w) : bflo(w); C[e] = sp * C[e] + sl * cl; } }
.LBB0_356:
	s_or_b64 exec, exec, s[20:21]
	v_sub_f32_e32 v27, v51, v28
	v_sub_f32_e32 v26, v26, v28
	v_mul_f32_e32 v27, 0x3fb8aa3b, v27
	v_mul_f32_e32 v26, 0x3fb8aa3b, v26
	v_exp_f32_e32 v38, v27
	v_exp_f32_e32 v40, v26
	v_lshlrev_b32_e32 v26, 16, v20
	v_and_b32_e32 v27, 0xffff0000, v20
	v_lshlrev_b32_e32 v20, 16, v21
	v_and_b32_e32 v21, 0xffff0000, v21
	v_pk_mul_f32 v[20:21], v[38:39], v[20:21] op_sel_hi:[0,1]
	v_pk_fma_f32 v[16:17], v[16:17], v[40:41], v[20:21] op_sel_hi:[1,0,1]
	v_lshlrev_b32_e32 v20, 16, v22
	v_and_b32_e32 v21, 0xffff0000, v22
	v_lshlrev_b32_e32 v22, 16, v23
	v_and_b32_e32 v23, 0xffff0000, v23
	v_pk_mul_f32 v[26:27], v[38:39], v[26:27] op_sel_hi:[0,1]
	v_pk_mul_f32 v[20:21], v[38:39], v[20:21] op_sel_hi:[0,1]
	v_pk_mul_f32 v[22:23], v[38:39], v[22:23] op_sel_hi:[0,1]
	v_pk_fma_f32 v[26:27], v[30:31], v[40:41], v[26:27] op_sel_hi:[1,0,1]
	v_pk_fma_f32 v[20:21], v[24:25], v[40:41], v[20:21] op_sel_hi:[1,0,1]
	v_pk_fma_f32 v[18:19], v[18:19], v[40:41], v[22:23] op_sel_hi:[1,0,1]
	s_and_saveexec_b64 s[20:21], vcc
	s_cbranch_execz .LBB0_358
	v_mad_u64_u32 v[30:31], s[18:19], s18, v59, v[32:33]
	v_cvt_pk_bf16_f32 v25, v18, v19
	v_cvt_pk_bf16_f32 v24, v20, v21
	v_cvt_pk_bf16_f32 v23, v16, v17
	v_cvt_pk_bf16_f32 v22, v26, v27
	v_add_u32_e32 v31, s61, v31
	global_store_dwordx4 v[30:31], v[22:25], off nt

; DI unsigned pk2(float lo, float hi) { const f32n2 v = {lo, hi}; return __builtin_bit_cast(unsigned, __builtin_convertvector(v, bf16n2)); }
; DI float bflo(unsigned w) { return __uint_as_float(w << 16); }
; DI float bfhi(unsigned w) { return __uint_as_float(w & 0xffff0000u); }
; DI void scan_item(const Ctx& c, int st, int slice, int lane) {
;     ...
;         for (int u = 0; u < 8; ++u) { const int ch = d ? chunk0 + nch - 1 - (i0 + u) : chunk0 + i0 + u; const size_t ti = (size_t)(d * NCHUNK + ch) * 4 + head;
;             if (slice == 0 && lane == 0) MP[ti] = m;
;             u32x4 o; o.x = pk2(C[0], C[1]); o.y = pk2(C[2], C[3]); o.z = pk2(C[4], C[5]); o.w = pk2(C[6], C[7]);
;             if (act) *(u32x4*)(CST + ti * ST_ELEMS + e0) = o;
;             const float mn = fmaxf(bt[u] + m, ml[u]), sp = __expf(bt[u] + m - mn), sl = __expf(ml[u] - mn); m = mn;
; #pragma unroll
;             for (int e = 0; e < 8; ++e) { const unsigned w = ld[u][e >> 1]; const float cl = (e & 1) ? bfhi(w) : bflo(w); C[e] = sp * C[e] + sl * cl; } }
.LBB0_360:
	s_or_b64 exec, exec, s[18:19]
	v_sub_f32_e32 v23, v49, v24
	v_sub_f32_e32 v22, v22, v24
	v_mul_f32_e32 v23, 0x3fb8aa3b, v23
	v_mul_f32_e32 v22, 0x3fb8aa3b, v22
	v_exp_f32_e32 v28, v23
	v_exp_f32_e32 v30, v22
	v_lshlrev_b32_e32 v22, 16, v8
	v_and_b32_e32 v23, 0xffff0000, v8
	v_lshlrev_b32_e32 v8, 16, v9
	v_and_b32_e32 v9, 0xffff0000, v9
	v_pk_mul_f32 v[8:9], v[28:29], v[8:9] op_sel_hi:[0,1]
	v_pk_fma_f32 v[8:9], v[16:17], v[30:31], v[8:9] op_sel_hi:[1,0,1]
	v_lshlrev_b32_e32 v16, 16, v10
	v_and_b32_e32 v17, 0xffff0000, v10
	v_lshlrev_b32_e32 v10, 16, v11
	v_and_b32_e32 v11, 0xffff0000, v11
	v_pk_mul_f32 v[22:23], v[28:29], v[22:23] op_sel_hi:[0,1]
	v_pk_mul_f32 v[16:17], v[28:29], v[16:17] op_sel_hi:[0,1]
	v_pk_mul_f32 v[10:11], v[28:29], v[10:11] op_sel_hi:[0,1]
	v_pk_fma_f32 v[22:23], v[26:27], v[30:31], v[22:23] op_sel_hi:[1,0,1]
	v_pk_fma_f32 v[16:17], v[20:21], v[30:31], v[16:17] op_sel_hi:[1,0,1]
	v_pk_fma_f32 v[10:11], v[18:19], v[30:31], v[10:11] op_sel_hi:[1,0,1]
	s_and_saveexec_b64 s[18:19], vcc
	s_cbranch_execz .LBB0_362
	v_mad_u64_u32 v[26:27], s[16:17], s16, v59, v[32:33]
	v_cvt_pk_bf16_f32 v21, v10, v11
	v_cvt_pk_bf16_f32 v20, v16, v17
	v_cvt_pk_bf16_f32 v19, v8, v9
	v_cvt_pk_bf16_f32 v18, v22, v23
	v_add_u32_e32 v27, s60, v27
	global_store_dwordx4 v[26:27], v[18:21], off nt

; DI unsigned pk2(float lo, float hi) { const f32n2 v = {lo, hi}; return __builtin_bit_cast(unsigned, __builtin_convertvector(v, bf16n2)); }
; DI float bflo(unsigned w) { return __uint_as_float(w << 16); }
; DI float bfhi(unsigned w) { return __uint_as_float(w & 0xffff0000u); }
; DI void scan_item(const Ctx& c, int st, int slice, int lane) {
;     ...
;         for (int u = 0; u < 8; ++u) { const int ch = d ? chunk0 + nch - 1 - (i0 + u) : chunk0 + i0 + u; const size_t ti = (size_t)(d * NCHUNK + ch) * 4 + head;
;             if (slice == 0 && lane == 0) MP[ti] = m;
;             u32x4 o; o.x = pk2(C[0], C[1]); o.y = pk2(C[2], C[3]); o.z = pk2(C[4], C[5]); o.w = pk2(C[6], C[7]);
;             if (act) *(u32x4*)(CST + ti * ST_ELEMS + e0) = o;
;             const float mn = fmaxf(bt[u] + m, ml[u]), sp = __expf(bt[u] + m - mn), sl = __expf(ml[u] - mn); m = mn;
; #pragma unroll
;             for (int e = 0; e < 8; ++e) { const unsigned w = ld[u][e >> 1]; const float cl = (e & 1) ? bfhi(w) : bflo(w); C[e] = sp * C[e] + sl * cl; } }
.LBB0_364:
	s_or_b64 exec, exec, s[16:17]
	v_sub_f32_e32 v19, v47, v20
	v_sub_f32_e32 v18, v18, v20
	v_mul_f32_e32 v19, 0x3fb8aa3b, v19
	v_mul_f32_e32 v18, 0x3fb8aa3b, v18
	v_exp_f32_e32 v24, v19
	v_exp_f32_e32 v26, v18
	v_lshlrev_b32_e32 v18, 16, v12
	v_and_b32_e32 v19, 0xffff0000, v12
	v_lshlrev_b32_e32 v12, 16, v13
	v_and_b32_e32 v13, 0xffff0000, v13
	v_pk_mul_f32 v[12:13], v[24:25], v[12:13] op_sel_hi:[0,1]
	v_pk_fma_f32 v[8:9], v[8:9], v[26:27], v[12:13] op_sel_hi:[1,0,1]
	v_lshlrev_b32_e32 v12, 16, v14
	v_and_b32_e32 v13, 0xffff0000, v14
	v_lshlrev_b32_e32 v14, 16, v15
	v_and_b32_e32 v15, 0xffff0000, v15
	v_pk_mul_f32 v[18:19], v[24:25], v[18:19] op_sel_hi:[0,1]
	v_pk_mul_f32 v[12:13], v[24:25], v[12:13] op_sel_hi:[0,1]
	v_pk_mul_f32 v[14:15], v[24:25], v[14:15] op_sel_hi:[0,1]
	v_pk_fma_f32 v[18:19], v[22:23], v[26:27], v[18:19] op_sel_hi:[1,0,1]
	v_pk_fma_f32 v[12:13], v[16:17], v[26:27], v[12:13] op_sel_hi:[1,0,1]
	v_pk_fma_f32 v[10:11], v[10:11], v[26:27], v[14:15] op_sel_hi:[1,0,1]
	s_and_saveexec_b64 s[16:17], vcc
	s_cbranch_execz .LBB0_366
	v_mad_u64_u32 v[22:23], s[14:15], s14, v59, v[32:33]
	v_cvt_pk_bf16_f32 v17, v10, v11
	v_cvt_pk_bf16_f32 v16, v12, v13
	v_cvt_pk_bf16_f32 v15, v8, v9
	v_cvt_pk_bf16_f32 v14, v18, v19
	v_add_u32_e32 v23, s59, v23
	global_store_dwordx4 v[22:23], v[14:17], off nt

; DI unsigned pk2(float lo, float hi) { const f32n2 v = {lo, hi}; return __builtin_bit_cast(unsigned, __builtin_convertvector(v, bf16n2)); }
; DI float bflo(unsigned w) { return __uint_as_float(w << 16); }
; DI float bfhi(unsigned w) { return __uint_as_float(w & 0xffff0000u); }
; DI void scan_item(const Ctx& c, int st, int slice, int lane) {
;     ...
;         for (int u = 0; u < 8; ++u) { const int ch = d ? chunk0 + nch - 1 - (i0 + u) : chunk0 + i0 + u; const size_t ti = (size_t)(d * NCHUNK + ch) * 4 + head;
;             if (slice == 0 && lane == 0) MP[ti] = m;
;             u32x4 o; o.x = pk2(C[0], C[1]); o.y = pk2(C[2], C[3]); o.z = pk2(C[4], C[5]); o.w = pk2(C[6], C[7]);
;             if (act) *(u32x4*)(CST + ti * ST_ELEMS + e0) = o;
;             const float mn = fmaxf(bt[u] + m, ml[u]), sp = __expf(bt[u] + m - mn), sl = __expf(ml[u] - mn); m = mn;
; #pragma unroll
;             for (int e = 0; e < 8; ++e) { const unsigned w = ld[u][e >> 1]; const float cl = (e & 1) ? bfhi(w) : bflo(w); C[e] = sp * C[e] + sl * cl; } }
.LBB0_368:
	s_or_b64 exec, exec, s[14:15]
	v_sub_f32_e32 v15, v37, v16
	v_sub_f32_e32 v14, v14, v16
	v_mul_f32_e32 v15, 0x3fb8aa3b, v15
	v_mul_f32_e32 v14, 0x3fb8aa3b, v14
	v_exp_f32_e32 v20, v15
	v_exp_f32_e32 v22, v14
	v_lshlrev_b32_e32 v14, 16, v0
	v_and_b32_e32 v15, 0xffff0000, v0
	v_lshlrev_b32_e32 v0, 16, v1
	v_and_b32_e32 v1, 0xffff0000, v1
	v_pk_mul_f32 v[0:1], v[20:21], v[0:1] op_sel_hi:[0,1]
	v_pk_fma_f32 v[8:9], v[8:9], v[22:23], v[0:1] op_sel_hi:[1,0,1]
	v_lshlrev_b32_e32 v0, 16, v2
	v_and_b32_e32 v1, 0xffff0000, v2
	v_pk_mul_f32 v[0:1], v[20:21], v[0:1] op_sel_hi:[0,1]
	v_pk_fma_f32 v[12:13], v[12:13], v[22:23], v[0:1] op_sel_hi:[1,0,1]
	v_lshlrev_b32_e32 v0, 16, v3
	v_and_b32_e32 v1, 0xffff0000, v3
	v_pk_mul_f32 v[14:15], v[20:21], v[14:15] op_sel_hi:[0,1]
	v_pk_mul_f32 v[0:1], v[20:21], v[0:1] op_sel_hi:[0,1]
	v_pk_fma_f32 v[14:15], v[18:19], v[22:23], v[14:15] op_sel_hi:[1,0,1]
	v_pk_fma_f32 v[0:1], v[10:11], v[22:23], v[0:1] op_sel_hi:[1,0,1]
	s_and_saveexec_b64 s[14:15], vcc
	s_cbranch_execz .LBB0_321
	v_mad_u64_u32 v[2:3], s[12:13], s12, v59, v[32:33]
	v_cvt_pk_bf16_f32 v21, v0, v1
	v_cvt_pk_bf16_f32 v20, v12, v13
	v_cvt_pk_bf16_f32 v19, v8, v9
	v_cvt_pk_bf16_f32 v18, v14, v15
	v_add_u32_e32 v3, s58, v3
	global_store_dwordx4 v[2:3], v[18:21], off nt
	s_branch .LBB0_321

; DI void scan_item(const Ctx& c, int st, int slice, int lane) {
;     ...
;     for (int i0 = 0; i0 < nch; i0 += 8) {
;         u32x4 ld[8]; float bt[8], ml[8];
; #pragma unroll
;         for (int u = 0; u < 8; ++u) { const int ch = d ? chunk0 + nch - 1 - (i0 + u) : chunk0 + i0 + u; const size_t ti = (size_t)(d * NCHUNK + ch) * 4 + head;
;             ld[u] = act ? *(const u32x4*)(CST + ti * ST_ELEMS + e0) : (u32x4){0u, 0u, 0u, 0u}; bt[u] = CHSC[ti * 2]; ml[u] = CHSC[ti * 2 + 1]; }
.LBB0_378:
	s_add_i32 s40, s47, s53
	s_add_i32 s12, s40, 0x68
	s_and_b64 s[10:11], s[8:9], exec
	s_cselect_b32 s10, s12, s52
	s_add_i32 s10, s10, s50
	s_ashr_i32 s11, s10, 31
	s_lshl_b64 s[10:11], s[10:11], 2
	s_or_b64 s[34:35], s[10:11], s[6:7]
	v_mov_b32_e32 v20, 0
	s_mul_i32 s63, s35, 0x8100
	v_mov_b32_e32 v28, 0
	v_mov_b32_e32 v29, 0
	v_mov_b32_e32 v30, 0
	v_mov_b32_e32 v31, 0
	s_and_saveexec_b64 s[10:11], vcc
	s_cbranch_execz .LBB0_380
	v_mad_u64_u32 v[0:1], s[12:13], s34, v61, v[34:35]
	v_add_u32_e32 v1, s63, v1
	global_load_dwordx4 v[28:31], v[0:1], off nt
.LBB0_380:
	s_or_b64 exec, exec, s[10:11]
	s_add_i32 s53, s53, 8
	s_lshl_b64 s[10:11], s[34:35], 3
	s_add_u32 s10, s33, s10
	s_addc_u32 s11, s44, s11
	global_load_dwordx2 v[58:59], v20, s[10:11]
	s_xor_b32 s10, s53, -2
	s_add_i32 s12, s10, s51
	s_add_i32 s13, s40, 0x69
	s_and_b64 s[10:11], s[8:9], exec
	s_cselect_b32 s10, s13, s12
	s_add_i32 s10, s10, s50
	s_ashr_i32 s11, s10, 31
	s_lshl_b64 s[10:11], s[10:11], 2
	s_or_b64 s[30:31], s[10:11], s[6:7]
	s_mul_i32 s62, s31, 0x8100
	v_mov_b32_e32 v21, 0
	v_mov_b32_e32 v22, 0
	v_mov_b32_e32 v23, 0
	s_and_saveexec_b64 s[10:11], vcc
	s_cbranch_execz .LBB0_382
	v_mad_u64_u32 v[0:1], s[12:13], s30, v61, v[34:35]
	v_add_u32_e32 v1, s62, v1
	global_load_dwordx4 v[20:23], v[0:1], off nt
.LBB0_382:
	s_or_b64 exec, exec, s[10:11]
	s_lshl_b64 s[10:11], s[30:31], 3
	s_add_u32 s10, s33, s10
	s_addc_u32 s11, s44, s11
	v_mov_b32_e32 v12, 0
	global_load_dwordx2 v[56:57], v12, s[10:11]
	s_xor_b32 s10, s53, -3
	s_add_i32 s12, s10, s51
	s_add_i32 s13, s40, 0x6a
	s_and_b64 s[10:11], s[8:9], exec
	s_cselect_b32 s10, s13, s12
	s_add_i32 s10, s10, s50
	s_ashr_i32 s11, s10, 31
	s_lshl_b64 s[10:11], s[10:11], 2
	s_or_b64 s[20:21], s[10:11], s[6:7]
	s_mul_i32 s61, s21, 0x8100
	v_mov_b32_e32 v24, 0
	v_mov_b32_e32 v25, 0
	v_mov_b32_e32 v26, 0
	v_mov_b32_e32 v27, 0
	s_and_saveexec_b64 s[10:11], vcc
	s_cbranch_execz .LBB0_384
	v_mad_u64_u32 v[0:1], s[12:13], s20, v61, v[34:35]
	v_add_u32_e32 v1, s61, v1
	global_load_dwordx4 v[24:27], v[0:1], off nt
.LBB0_384:
	s_or_b64 exec, exec, s[10:11]
	s_lshl_b64 s[10:11], s[20:21], 3
	s_add_u32 s10, s33, s10
	s_addc_u32 s11, s44, s11
	global_load_dwordx2 v[54:55], v12, s[10:11]
	s_xor_b32 s10, s53, -4
	s_add_i32 s12, s10, s51
	s_add_i32 s13, s40, 0x6b
	s_and_b64 s[10:11], s[8:9], exec
	s_cselect_b32 s10, s13, s12
	s_add_i32 s10, s10, s50
	s_ashr_i32 s11, s10, 31
	s_lshl_b64 s[10:11], s[10:11], 2
	s_or_b64 s[18:19], s[10:11], s[6:7]
	s_mul_i32 s60, s19, 0x8100
	v_mov_b32_e32 v13, 0
	v_mov_b32_e32 v14, 0
	v_mov_b32_e32 v15, 0
	s_and_saveexec_b64 s[10:11], vcc
	s_cbranch_execz .LBB0_386
	v_mad_u64_u32 v[0:1], s[12:13], s18, v61, v[34:35]
	v_add_u32_e32 v1, s60, v1
	global_load_dwordx4 v[12:15], v[0:1], off nt
.LBB0_386:
	s_or_b64 exec, exec, s[10:11]
	s_lshl_b64 s[10:11], s[18:19], 3
	s_add_u32 s10, s33, s10
	s_addc_u32 s11, s44, s11
	v_mov_b32_e32 v4, 0
	global_load_dwordx2 v[52:53], v4, s[10:11]
	s_xor_b32 s10, s53, -5
	s_add_i32 s12, s10, s51
	s_add_i32 s13, s40, 0x6c
	s_and_b64 s[10:11], s[8:9], exec
	s_cselect_b32 s10, s13, s12
	s_add_i32 s10, s10, s50
	s_ashr_i32 s11, s10, 31
	s_lshl_b64 s[10:11], s[10:11], 2
	s_or_b64 s[16:17], s[10:11], s[6:7]
	s_mul_i32 s59, s17, 0x8100
	v_mov_b32_e32 v16, 0
	v_mov_b32_e32 v17, 0
	v_mov_b32_e32 v18, 0
	v_mov_b32_e32 v19, 0
	s_and_saveexec_b64 s[10:11], vcc
	s_cbranch_execz .LBB0_388
	v_mad_u64_u32 v[0:1], s[12:13], s16, v61, v[34:35]
	v_add_u32_e32 v1, s59, v1
	global_load_dwordx4 v[16:19], v[0:1], off nt
.LBB0_388:
	s_or_b64 exec, exec, s[10:11]
	s_lshl_b64 s[10:11], s[16:17], 3
	s_add_u32 s10, s33, s10
	s_addc_u32 s11, s44, s11
	global_load_dwordx2 v[50:51], v4, s[10:11]
	s_xor_b32 s10, s53, -6
	s_add_i32 s12, s10, s51
	s_add_i32 s13, s40, 0x6d
	s_and_b64 s[10:11], s[8:9], exec
	s_cselect_b32 s10, s13, s12
	s_add_i32 s10, s10, s50
	s_ashr_i32 s11, s10, 31
	s_lshl_b64 s[10:11], s[10:11], 2
	s_or_b64 s[14:15], s[10:11], s[6:7]
	s_mul_i32 s58, s15, 0x8100
	v_mov_b32_e32 v5, 0
	v_mov_b32_e32 v6, 0
	v_mov_b32_e32 v7, 0
	s_and_saveexec_b64 s[10:11], vcc
	s_cbranch_execz .LBB0_390
	v_mad_u64_u32 v[0:1], s[12:13], s14, v61, v[34:35]
	v_add_u32_e32 v1, s58, v1
	global_load_dwordx4 v[4:7], v[0:1], off nt
.LBB0_390:
	s_or_b64 exec, exec, s[10:11]
	s_lshl_b64 s[10:11], s[14:15], 3
	s_add_u32 s10, s33, s10
	s_addc_u32 s11, s44, s11
	v_mov_b32_e32 v0, 0
	global_load_dwordx2 v[42:43], v0, s[10:11]
	s_xor_b32 s10, s53, -7
	s_add_i32 s12, s10, s51
	s_add_i32 s13, s40, 0x6e
	s_and_b64 s[10:11], s[8:9], exec
	s_cselect_b32 s10, s13, s12
	s_add_i32 s10, s10, s50
	s_ashr_i32 s11, s10, 31
	s_lshl_b64 s[10:11], s[10:11], 2
	s_or_b64 s[12:13], s[10:11], s[6:7]
	s_mul_i32 s55, s13, 0x8100
	v_mov_b32_e32 v8, 0
	v_mov_b32_e32 v9, 0
	v_mov_b32_e32 v10, 0
	v_mov_b32_e32 v11, 0
	s_and_saveexec_b64 s[10:11], vcc
	s_cbranch_execz .LBB0_392
	v_mad_u64_u32 v[2:3], s[64:65], s12, v61, v[34:35]
	v_add_u32_e32 v3, s55, v3
	global_load_dwordx4 v[8:11], v[2:3], off nt
.LBB0_392:
	s_or_b64 exec, exec, s[10:11]
	s_lshl_b64 s[10:11], s[12:13], 3
	s_add_u32 s10, s33, s10
	s_addc_u32 s11, s44, s11
	global_load_dwordx2 v[38:39], v0, s[10:11]
	s_xor_b32 s10, s53, -8
	s_add_i32 s41, s10, s51
	s_addk_i32 s40, 0x6f
	s_and_b64 s[10:11], s[8:9], exec
	s_cselect_b32 s10, s40, s41
	s_add_i32 s10, s10, s50
	s_ashr_i32 s11, s10, 31
	s_lshl_b64 s[10:11], s[10:11], 2
	s_or_b64 s[10:11], s[10:11], s[6:7]
	s_mul_i32 s54, s11, 0x8100
	v_mov_b32_e32 v1, 0
	v_mov_b32_e32 v2, 0
	v_mov_b32_e32 v3, 0
	s_and_saveexec_b64 s[40:41], vcc
	s_cbranch_execz .LBB0_394
	v_mad_u64_u32 v[0:1], s[64:65], s10, v61, v[34:35]
	v_add_u32_e32 v1, s54, v1
	global_load_dwordx4 v[0:3], v[0:1], off nt

; DI unsigned pk2(float lo, float hi) { const f32n2 v = {lo, hi}; return __builtin_bit_cast(unsigned, __builtin_convertvector(v, bf16n2)); }
; DI void scan_item(const Ctx& c, int st, int slice, int lane) {
;     ...
;         for (int u = 0; u < 8; ++u) { const int ch = d ? chunk0 + nch - 1 - (i0 + u) : chunk0 + i0 + u; const size_t ti = (size_t)(d * NCHUNK + ch) * 4 + head;
;             if (slice == 0 && lane == 0) MP[ti] = m;
;             u32x4 o; o.x = pk2(C[0], C[1]); o.y = pk2(C[2], C[3]); o.z = pk2(C[4], C[5]); o.w = pk2(C[6], C[7]);
;             if (act) *(u32x4*)(CST + ti * ST_ELEMS + e0) = o;
.LBB0_396:
	s_or_b64 exec, exec, s[40:41]
	s_and_saveexec_b64 s[40:41], s[0:1]
	s_xor_b64 s[40:41], exec, s[40:41]
	s_andn2_saveexec_b64 s[40:41], s[40:41]
	s_cbranch_execz .LBB0_398
	v_mad_u64_u32 v[66:67], s[34:35], s34, v61, v[34:35]
	v_cvt_pk_bf16_f32 v65, v48, v49
	v_cvt_pk_bf16_f32 v64, v46, v47
	v_cvt_pk_bf16_f32 v63, v44, v45
	v_cvt_pk_bf16_f32 v62, v40, v41
	v_add_u32_e32 v67, s63, v67
	global_store_dwordx4 v[66:67], v[62:65], off nt

; DI unsigned pk2(float lo, float hi) { const f32n2 v = {lo, hi}; return __builtin_bit_cast(unsigned, __builtin_convertvector(v, bf16n2)); }
; DI float bflo(unsigned w) { return __uint_as_float(w << 16); }
; DI float bfhi(unsigned w) { return __uint_as_float(w & 0xffff0000u); }
; DI void scan_item(const Ctx& c, int st, int slice, int lane) {
;     ...
;         for (int u = 0; u < 8; ++u) { const int ch = d ? chunk0 + nch - 1 - (i0 + u) : chunk0 + i0 + u; const size_t ti = (size_t)(d * NCHUNK + ch) * 4 + head;
;             if (slice == 0 && lane == 0) MP[ti] = m;
;             u32x4 o; o.x = pk2(C[0], C[1]); o.y = pk2(C[2], C[3]); o.z = pk2(C[4], C[5]); o.w = pk2(C[6], C[7]);
;             if (act) *(u32x4*)(CST + ti * ST_ELEMS + e0) = o;
;             const float mn = fmaxf(bt[u] + m, ml[u]), sp = __expf(bt[u] + m - mn), sl = __expf(ml[u] - mn); m = mn;
; #pragma unroll
;             for (int e = 0; e < 8; ++e) { const unsigned w = ld[u][e >> 1]; const float cl = (e & 1) ? bfhi(w) : bflo(w); C[e] = sp * C[e] + sl * cl; } }
.LBB0_400:
	s_or_b64 exec, exec, s[34:35]
	v_sub_f32_e32 v58, v58, v32
	v_mul_f32_e32 v62, 0x3fb8aa3b, v58
	v_sub_f32_e32 v58, v59, v32
	v_mul_f32_e32 v58, 0x3fb8aa3b, v58
	v_exp_f32_e32 v58, v58
	v_exp_f32_e32 v62, v62
	v_lshlrev_b32_e32 v64, 16, v28
	v_and_b32_e32 v65, 0xffff0000, v28
	v_lshlrev_b32_e32 v28, 16, v29
	v_and_b32_e32 v29, 0xffff0000, v29
	v_pk_mul_f32 v[28:29], v[58:59], v[28:29] op_sel_hi:[0,1]
	v_pk_fma_f32 v[28:29], v[44:45], v[62:63], v[28:29] op_sel_hi:[1,0,1]
	v_lshlrev_b32_e32 v44, 16, v30
	v_and_b32_e32 v45, 0xffff0000, v30
	v_lshlrev_b32_e32 v30, 16, v31
	v_and_b32_e32 v31, 0xffff0000, v31
	v_pk_mul_f32 v[64:65], v[58:59], v[64:65] op_sel_hi:[0,1]
	v_pk_mul_f32 v[44:45], v[58:59], v[44:45] op_sel_hi:[0,1]
	v_pk_mul_f32 v[30:31], v[58:59], v[30:31] op_sel_hi:[0,1]
	v_pk_fma_f32 v[40:41], v[40:41], v[62:63], v[64:65] op_sel_hi:[1,0,1]
	v_pk_fma_f32 v[44:45], v[46:47], v[62:63], v[44:45] op_sel_hi:[1,0,1]
	v_pk_fma_f32 v[30:31], v[48:49], v[62:63], v[30:31] op_sel_hi:[1,0,1]
	s_and_saveexec_b64 s[34:35], vcc
	s_cbranch_execz .LBB0_402
	v_mad_u64_u32 v[58:59], s[30:31], s30, v61, v[34:35]
	v_cvt_pk_bf16_f32 v49, v30, v31
	v_cvt_pk_bf16_f32 v48, v44, v45
	v_cvt_pk_bf16_f32 v47, v28, v29
	v_cvt_pk_bf16_f32 v46, v40, v41
	v_add_u32_e32 v59, s62, v59
	global_store_dwordx4 v[58:59], v[46:49], off nt

; DI unsigned pk2(float lo, float hi) { const f32n2 v = {lo, hi}; return __builtin_bit_cast(unsigned, __builtin_convertvector(v, bf16n2)); }
; DI float bflo(unsigned w) { return __uint_as_float(w << 16); }
; DI float bfhi(unsigned w) { return __uint_as_float(w & 0xffff0000u); }
; DI void scan_item(const Ctx& c, int st, int slice, int lane) {
;     ...
;         for (int u = 0; u < 8; ++u) { const int ch = d ? chunk0 + nch - 1 - (i0 + u) : chunk0 + i0 + u; const size_t ti = (size_t)(d * NCHUNK + ch) * 4 + head;
;             if (slice == 0 && lane == 0) MP[ti] = m;
;             u32x4 o; o.x = pk2(C[0], C[1]); o.y = pk2(C[2], C[3]); o.z = pk2(C[4], C[5]); o.w = pk2(C[6], C[7]);
;             if (act) *(u32x4*)(CST + ti * ST_ELEMS + e0) = o;
;             const float mn = fmaxf(bt[u] + m, ml[u]), sp = __expf(bt[u] + m - mn), sl = __expf(ml[u] - mn); m = mn;
; #pragma unroll
;             for (int e = 0; e < 8; ++e) { const unsigned w = ld[u][e >> 1]; const float cl = (e & 1) ? bfhi(w) : bflo(w); C[e] = sp * C[e] + sl * cl; } }
.LBB0_404:
	s_or_b64 exec, exec, s[30:31]
	v_sub_f32_e32 v46, v46, v32
	v_mul_f32_e32 v47, 0x3fb8aa3b, v46
	v_sub_f32_e32 v46, v57, v32
	v_mul_f32_e32 v46, 0x3fb8aa3b, v46
	v_exp_f32_e32 v46, v46
	v_exp_f32_e32 v48, v47
	v_lshlrev_b32_e32 v56, 16, v20
	v_and_b32_e32 v57, 0xffff0000, v20
	v_lshlrev_b32_e32 v20, 16, v21
	v_and_b32_e32 v21, 0xffff0000, v21
	v_pk_mul_f32 v[20:21], v[46:47], v[20:21] op_sel_hi:[0,1]
	v_pk_fma_f32 v[20:21], v[28:29], v[48:49], v[20:21] op_sel_hi:[1,0,1]
	v_lshlrev_b32_e32 v28, 16, v22
	v_and_b32_e32 v29, 0xffff0000, v22
	v_lshlrev_b32_e32 v22, 16, v23
	v_and_b32_e32 v23, 0xffff0000, v23
	v_pk_mul_f32 v[56:57], v[46:47], v[56:57] op_sel_hi:[0,1]
	v_pk_mul_f32 v[28:29], v[46:47], v[28:29] op_sel_hi:[0,1]
	v_pk_mul_f32 v[22:23], v[46:47], v[22:23] op_sel_hi:[0,1]
	v_pk_fma_f32 v[40:41], v[40:41], v[48:49], v[56:57] op_sel_hi:[1,0,1]
	v_pk_fma_f32 v[28:29], v[44:45], v[48:49], v[28:29] op_sel_hi:[1,0,1]
	v_pk_fma_f32 v[22:23], v[30:31], v[48:49], v[22:23] op_sel_hi:[1,0,1]
	s_and_saveexec_b64 s[30:31], vcc
	s_cbranch_execz .LBB0_406
	v_mad_u64_u32 v[30:31], s[20:21], s20, v61, v[34:35]
	v_cvt_pk_bf16_f32 v47, v22, v23
	v_cvt_pk_bf16_f32 v46, v28, v29
	v_cvt_pk_bf16_f32 v45, v20, v21
	v_cvt_pk_bf16_f32 v44, v40, v41
	v_add_u32_e32 v31, s61, v31
	global_store_dwordx4 v[30:31], v[44:47], off nt

; DI unsigned pk2(float lo, float hi) { const f32n2 v = {lo, hi}; return __builtin_bit_cast(unsigned, __builtin_convertvector(v, bf16n2)); }
; DI float bflo(unsigned w) { return __uint_as_float(w << 16); }
; DI float bfhi(unsigned w) { return __uint_as_float(w & 0xffff0000u); }
; DI void scan_item(const Ctx& c, int st, int slice, int lane) {
;     ...
;         for (int u = 0; u < 8; ++u) { const int ch = d ? chunk0 + nch - 1 - (i0 + u) : chunk0 + i0 + u; const size_t ti = (size_t)(d * NCHUNK + ch) * 4 + head;
;             if (slice == 0 && lane == 0) MP[ti] = m;
;             u32x4 o; o.x = pk2(C[0], C[1]); o.y = pk2(C[2], C[3]); o.z = pk2(C[4], C[5]); o.w = pk2(C[6], C[7]);
;             if (act) *(u32x4*)(CST + ti * ST_ELEMS + e0) = o;
;             const float mn = fmaxf(bt[u] + m, ml[u]), sp = __expf(bt[u] + m - mn), sl = __expf(ml[u] - mn); m = mn;
; #pragma unroll
;             for (int e = 0; e < 8; ++e) { const unsigned w = ld[u][e >> 1]; const float cl = (e & 1) ? bfhi(w) : bflo(w); C[e] = sp * C[e] + sl * cl; } }
.LBB0_408:
	s_or_b64 exec, exec, s[20:21]
	v_sub_f32_e32 v31, v55, v32
	v_sub_f32_e32 v30, v30, v32
	v_mul_f32_e32 v31, 0x3fb8aa3b, v31
	v_mul_f32_e32 v30, 0x3fb8aa3b, v30
	v_exp_f32_e32 v44, v31
	v_exp_f32_e32 v46, v30
	v_lshlrev_b32_e32 v30, 16, v24
	v_and_b32_e32 v31, 0xffff0000, v24
	v_lshlrev_b32_e32 v24, 16, v25
	v_and_b32_e32 v25, 0xffff0000, v25
	v_pk_mul_f32 v[24:25], v[44:45], v[24:25] op_sel_hi:[0,1]
	v_pk_fma_f32 v[20:21], v[20:21], v[46:47], v[24:25] op_sel_hi:[1,0,1]
	v_lshlrev_b32_e32 v24, 16, v26
	v_and_b32_e32 v25, 0xffff0000, v26
	v_lshlrev_b32_e32 v26, 16, v27
	v_and_b32_e32 v27, 0xffff0000, v27
	v_pk_mul_f32 v[30:31], v[44:45], v[30:31] op_sel_hi:[0,1]
	v_pk_mul_f32 v[24:25], v[44:45], v[24:25] op_sel_hi:[0,1]
	v_pk_mul_f32 v[26:27], v[44:45], v[26:27] op_sel_hi:[0,1]
	v_pk_fma_f32 v[30:31], v[40:41], v[46:47], v[30:31] op_sel_hi:[1,0,1]
	v_pk_fma_f32 v[24:25], v[28:29], v[46:47], v[24:25] op_sel_hi:[1,0,1]
	v_pk_fma_f32 v[22:23], v[22:23], v[46:47], v[26:27] op_sel_hi:[1,0,1]
	s_and_saveexec_b64 s[20:21], vcc
	s_cbranch_execz .LBB0_410
	v_mad_u64_u32 v[40:41], s[18:19], s18, v61, v[34:35]
	v_cvt_pk_bf16_f32 v29, v22, v23
	v_cvt_pk_bf16_f32 v28, v24, v25
	v_cvt_pk_bf16_f32 v27, v20, v21
	v_cvt_pk_bf16_f32 v26, v30, v31
	v_add_u32_e32 v41, s60, v41
	global_store_dwordx4 v[40:41], v[26:29], off nt

; DI unsigned pk2(float lo, float hi) { const f32n2 v = {lo, hi}; return __builtin_bit_cast(unsigned, __builtin_convertvector(v, bf16n2)); }
; DI float bflo(unsigned w) { return __uint_as_float(w << 16); }
; DI float bfhi(unsigned w) { return __uint_as_float(w & 0xffff0000u); }
; DI void scan_item(const Ctx& c, int st, int slice, int lane) {
;     ...
;         for (int u = 0; u < 8; ++u) { const int ch = d ? chunk0 + nch - 1 - (i0 + u) : chunk0 + i0 + u; const size_t ti = (size_t)(d * NCHUNK + ch) * 4 + head;
;             if (slice == 0 && lane == 0) MP[ti] = m;
;             u32x4 o; o.x = pk2(C[0], C[1]); o.y = pk2(C[2], C[3]); o.z = pk2(C[4], C[5]); o.w = pk2(C[6], C[7]);
;             if (act) *(u32x4*)(CST + ti * ST_ELEMS + e0) = o;
;             const float mn = fmaxf(bt[u] + m, ml[u]), sp = __expf(bt[u] + m - mn), sl = __expf(ml[u] - mn); m = mn;
; #pragma unroll
;             for (int e = 0; e < 8; ++e) { const unsigned w = ld[u][e >> 1]; const float cl = (e & 1) ? bfhi(w) : bflo(w); C[e] = sp * C[e] + sl * cl; } }
.LBB0_412:
	s_or_b64 exec, exec, s[18:19]
	v_sub_f32_e32 v27, v53, v28
	v_sub_f32_e32 v26, v26, v28
	v_mul_f32_e32 v27, 0x3fb8aa3b, v27
	v_mul_f32_e32 v26, 0x3fb8aa3b, v26
	v_exp_f32_e32 v32, v27
	v_exp_f32_e32 v40, v26
	v_lshlrev_b32_e32 v26, 16, v12
	v_and_b32_e32 v27, 0xffff0000, v12
	v_lshlrev_b32_e32 v12, 16, v13
	v_and_b32_e32 v13, 0xffff0000, v13
	v_pk_mul_f32 v[12:13], v[32:33], v[12:13] op_sel_hi:[0,1]
	v_pk_fma_f32 v[12:13], v[20:21], v[40:41], v[12:13] op_sel_hi:[1,0,1]
	v_lshlrev_b32_e32 v20, 16, v14
	v_and_b32_e32 v21, 0xffff0000, v14
	v_lshlrev_b32_e32 v14, 16, v15
	v_and_b32_e32 v15, 0xffff0000, v15
	v_pk_mul_f32 v[26:27], v[32:33], v[26:27] op_sel_hi:[0,1]
	v_pk_mul_f32 v[20:21], v[32:33], v[20:21] op_sel_hi:[0,1]
	v_pk_mul_f32 v[14:15], v[32:33], v[14:15] op_sel_hi:[0,1]
	v_pk_fma_f32 v[26:27], v[30:31], v[40:41], v[26:27] op_sel_hi:[1,0,1]
	v_pk_fma_f32 v[20:21], v[24:25], v[40:41], v[20:21] op_sel_hi:[1,0,1]
	v_pk_fma_f32 v[14:15], v[22:23], v[40:41], v[14:15] op_sel_hi:[1,0,1]
	s_and_saveexec_b64 s[18:19], vcc
	s_cbranch_execz .LBB0_414
	v_mad_u64_u32 v[30:31], s[16:17], s16, v61, v[34:35]
	v_cvt_pk_bf16_f32 v25, v14, v15
	v_cvt_pk_bf16_f32 v24, v20, v21
	v_cvt_pk_bf16_f32 v23, v12, v13
	v_cvt_pk_bf16_f32 v22, v26, v27
	v_add_u32_e32 v31, s59, v31
	global_store_dwordx4 v[30:31], v[22:25], off nt

; DI unsigned pk2(float lo, float hi) { const f32n2 v = {lo, hi}; return __builtin_bit_cast(unsigned, __builtin_convertvector(v, bf16n2)); }
; DI float bflo(unsigned w) { return __uint_as_float(w << 16); }
; DI float bfhi(unsigned w) { return __uint_as_float(w & 0xffff0000u); }
; DI void scan_item(const Ctx& c, int st, int slice, int lane) {
;     ...
;         for (int u = 0; u < 8; ++u) { const int ch = d ? chunk0 + nch - 1 - (i0 + u) : chunk0 + i0 + u; const size_t ti = (size_t)(d * NCHUNK + ch) * 4 + head;
;             if (slice == 0 && lane == 0) MP[ti] = m;
;             u32x4 o; o.x = pk2(C[0], C[1]); o.y = pk2(C[2], C[3]); o.z = pk2(C[4], C[5]); o.w = pk2(C[6], C[7]);
;             if (act) *(u32x4*)(CST + ti * ST_ELEMS + e0) = o;
;             const float mn = fmaxf(bt[u] + m, ml[u]), sp = __expf(bt[u] + m - mn), sl = __expf(ml[u] - mn); m = mn;
; #pragma unroll
;             for (int e = 0; e < 8; ++e) { const unsigned w = ld[u][e >> 1]; const float cl = (e & 1) ? bfhi(w) : bflo(w); C[e] = sp * C[e] + sl * cl; } }
.LBB0_416:
	s_or_b64 exec, exec, s[16:17]
	v_sub_f32_e32 v23, v51, v24
	v_sub_f32_e32 v22, v22, v24
	v_mul_f32_e32 v23, 0x3fb8aa3b, v23
	v_mul_f32_e32 v22, 0x3fb8aa3b, v22
	v_exp_f32_e32 v28, v23
	v_exp_f32_e32 v30, v22
	v_lshlrev_b32_e32 v22, 16, v16
	v_and_b32_e32 v23, 0xffff0000, v16
	v_lshlrev_b32_e32 v16, 16, v17
	v_and_b32_e32 v17, 0xffff0000, v17
	v_pk_mul_f32 v[16:17], v[28:29], v[16:17] op_sel_hi:[0,1]
	v_pk_fma_f32 v[12:13], v[12:13], v[30:31], v[16:17] op_sel_hi:[1,0,1]
	v_lshlrev_b32_e32 v16, 16, v18
	v_and_b32_e32 v17, 0xffff0000, v18
	v_lshlrev_b32_e32 v18, 16, v19
	v_and_b32_e32 v19, 0xffff0000, v19
	v_pk_mul_f32 v[22:23], v[28:29], v[22:23] op_sel_hi:[0,1]
	v_pk_mul_f32 v[16:17], v[28:29], v[16:17] op_sel_hi:[0,1]
	v_pk_mul_f32 v[18:19], v[28:29], v[18:19] op_sel_hi:[0,1]
	v_pk_fma_f32 v[22:23], v[26:27], v[30:31], v[22:23] op_sel_hi:[1,0,1]
	v_pk_fma_f32 v[16:17], v[20:21], v[30:31], v[16:17] op_sel_hi:[1,0,1]
	v_pk_fma_f32 v[14:15], v[14:15], v[30:31], v[18:19] op_sel_hi:[1,0,1]
	s_and_saveexec_b64 s[16:17], vcc
	s_cbranch_execz .LBB0_418
	v_mad_u64_u32 v[26:27], s[14:15], s14, v61, v[34:35]
	v_cvt_pk_bf16_f32 v21, v14, v15
	v_cvt_pk_bf16_f32 v20, v16, v17
	v_cvt_pk_bf16_f32 v19, v12, v13
	v_cvt_pk_bf16_f32 v18, v22, v23
	v_add_u32_e32 v27, s58, v27
	global_store_dwordx4 v[26:27], v[18:21], off nt

; DI unsigned pk2(float lo, float hi) { const f32n2 v = {lo, hi}; return __builtin_bit_cast(unsigned, __builtin_convertvector(v, bf16n2)); }
; DI float bflo(unsigned w) { return __uint_as_float(w << 16); }
; DI float bfhi(unsigned w) { return __uint_as_float(w & 0xffff0000u); }
; DI void scan_item(const Ctx& c, int st, int slice, int lane) {
;     ...
;         for (int u = 0; u < 8; ++u) { const int ch = d ? chunk0 + nch - 1 - (i0 + u) : chunk0 + i0 + u; const size_t ti = (size_t)(d * NCHUNK + ch) * 4 + head;
;             if (slice == 0 && lane == 0) MP[ti] = m;
;             u32x4 o; o.x = pk2(C[0], C[1]); o.y = pk2(C[2], C[3]); o.z = pk2(C[4], C[5]); o.w = pk2(C[6], C[7]);
;             if (act) *(u32x4*)(CST + ti * ST_ELEMS + e0) = o;
;             const float mn = fmaxf(bt[u] + m, ml[u]), sp = __expf(bt[u] + m - mn), sl = __expf(ml[u] - mn); m = mn;
; #pragma unroll
;             for (int e = 0; e < 8; ++e) { const unsigned w = ld[u][e >> 1]; const float cl = (e & 1) ? bfhi(w) : bflo(w); C[e] = sp * C[e] + sl * cl; } }
.LBB0_420:
	s_or_b64 exec, exec, s[14:15]
	v_sub_f32_e32 v19, v43, v20
	v_sub_f32_e32 v18, v18, v20
	v_mul_f32_e32 v19, 0x3fb8aa3b, v19
	v_mul_f32_e32 v18, 0x3fb8aa3b, v18
	v_exp_f32_e32 v24, v19
	v_exp_f32_e32 v26, v18
	v_lshlrev_b32_e32 v18, 16, v4
	v_and_b32_e32 v19, 0xffff0000, v4
	v_lshlrev_b32_e32 v4, 16, v5
	v_and_b32_e32 v5, 0xffff0000, v5
	v_pk_mul_f32 v[4:5], v[24:25], v[4:5] op_sel_hi:[0,1]
	v_pk_fma_f32 v[4:5], v[12:13], v[26:27], v[4:5] op_sel_hi:[1,0,1]
	v_lshlrev_b32_e32 v12, 16, v6
	v_and_b32_e32 v13, 0xffff0000, v6
	v_lshlrev_b32_e32 v6, 16, v7
	v_and_b32_e32 v7, 0xffff0000, v7
	v_pk_mul_f32 v[18:19], v[24:25], v[18:19] op_sel_hi:[0,1]
	v_pk_mul_f32 v[12:13], v[24:25], v[12:13] op_sel_hi:[0,1]
	v_pk_mul_f32 v[6:7], v[24:25], v[6:7] op_sel_hi:[0,1]
	v_pk_fma_f32 v[18:19], v[22:23], v[26:27], v[18:19] op_sel_hi:[1,0,1]
	v_pk_fma_f32 v[12:13], v[16:17], v[26:27], v[12:13] op_sel_hi:[1,0,1]
	v_pk_fma_f32 v[6:7], v[14:15], v[26:27], v[6:7] op_sel_hi:[1,0,1]
	s_and_saveexec_b64 s[14:15], vcc
	s_cbranch_execz .LBB0_422
	v_mad_u64_u32 v[22:23], s[12:13], s12, v61, v[34:35]
	v_cvt_pk_bf16_f32 v17, v6, v7
	v_cvt_pk_bf16_f32 v16, v12, v13
	v_cvt_pk_bf16_f32 v15, v4, v5
	v_cvt_pk_bf16_f32 v14, v18, v19
	v_add_u32_e32 v23, s55, v23
	global_store_dwordx4 v[22:23], v[14:17], off nt

; DI unsigned pk2(float lo, float hi) { const f32n2 v = {lo, hi}; return __builtin_bit_cast(unsigned, __builtin_convertvector(v, bf16n2)); }
; DI float bflo(unsigned w) { return __uint_as_float(w << 16); }
; DI float bfhi(unsigned w) { return __uint_as_float(w & 0xffff0000u); }
; DI void scan_item(const Ctx& c, int st, int slice, int lane) {
;     ...
;         for (int u = 0; u < 8; ++u) { const int ch = d ? chunk0 + nch - 1 - (i0 + u) : chunk0 + i0 + u; const size_t ti = (size_t)(d * NCHUNK + ch) * 4 + head;
;             if (slice == 0 && lane == 0) MP[ti] = m;
;             u32x4 o; o.x = pk2(C[0], C[1]); o.y = pk2(C[2], C[3]); o.z = pk2(C[4], C[5]); o.w = pk2(C[6], C[7]);
;             if (act) *(u32x4*)(CST + ti * ST_ELEMS + e0) = o;
;             const float mn = fmaxf(bt[u] + m, ml[u]), sp = __expf(bt[u] + m - mn), sl = __expf(ml[u] - mn); m = mn;
; #pragma unroll
;             for (int e = 0; e < 8; ++e) { const unsigned w = ld[u][e >> 1]; const float cl = (e & 1) ? bfhi(w) : bflo(w); C[e] = sp * C[e] + sl * cl; } }
.LBB0_424:
	s_or_b64 exec, exec, s[12:13]
	v_sub_f32_e32 v15, v39, v16
	v_sub_f32_e32 v14, v14, v16
	v_mul_f32_e32 v15, 0x3fb8aa3b, v15
	v_mul_f32_e32 v14, 0x3fb8aa3b, v14
	v_exp_f32_e32 v20, v15
	v_exp_f32_e32 v22, v14
	v_lshlrev_b32_e32 v14, 16, v8
	v_and_b32_e32 v15, 0xffff0000, v8
	v_lshlrev_b32_e32 v8, 16, v9
	v_and_b32_e32 v9, 0xffff0000, v9
	v_pk_mul_f32 v[8:9], v[20:21], v[8:9] op_sel_hi:[0,1]
	v_pk_fma_f32 v[8:9], v[4:5], v[22:23], v[8:9] op_sel_hi:[1,0,1]
	v_lshlrev_b32_e32 v4, 16, v10
	v_and_b32_e32 v5, 0xffff0000, v10
	v_pk_mul_f32 v[4:5], v[20:21], v[4:5] op_sel_hi:[0,1]
	v_pk_fma_f32 v[12:13], v[12:13], v[22:23], v[4:5] op_sel_hi:[1,0,1]
	v_lshlrev_b32_e32 v4, 16, v11
	v_and_b32_e32 v5, 0xffff0000, v11
	v_pk_mul_f32 v[14:15], v[20:21], v[14:15] op_sel_hi:[0,1]
	v_pk_mul_f32 v[4:5], v[20:21], v[4:5] op_sel_hi:[0,1]
	v_pk_fma_f32 v[14:15], v[18:19], v[22:23], v[14:15] op_sel_hi:[1,0,1]
	v_pk_fma_f32 v[4:5], v[6:7], v[22:23], v[4:5] op_sel_hi:[1,0,1]
	s_and_saveexec_b64 s[12:13], vcc
	s_cbranch_execz .LBB0_377
	v_mad_u64_u32 v[6:7], s[10:11], s10, v61, v[34:35]
	v_cvt_pk_bf16_f32 v21, v4, v5
	v_cvt_pk_bf16_f32 v20, v12, v13
	v_cvt_pk_bf16_f32 v19, v8, v9
	v_cvt_pk_bf16_f32 v18, v14, v15
	v_add_u32_e32 v7, s54, v7
	global_store_dwordx4 v[6:7], v[18:21], off nt
	s_branch .LBB0_377

; DI void scan_item(const Ctx& c, int st, int slice, int lane) {
;     ...
;     for (int i0 = 0; i0 < nch; i0 += 8) {
;         u32x4 ld[8]; float bt[8], ml[8];
; #pragma unroll
;         for (int u = 0; u < 8; ++u) { const int ch = d ? chunk0 + nch - 1 - (i0 + u) : chunk0 + i0 + u; const size_t ti = (size_t)(d * NCHUNK + ch) * 4 + head;
;             ld[u] = act ? *(const u32x4*)(CST + ti * ST_ELEMS + e0) : (u32x4){0u, 0u, 0u, 0u}; bt[u] = CHSC[ti * 2]; ml[u] = CHSC[ti * 2 + 1]; }
.LBB0_430:
	s_add_i32 s40, s43, s50
	s_and_b64 s[10:11], s[8:9], exec
	s_cselect_b32 s10, s40, s47
	s_add_i32 s10, s10, s45
	s_ashr_i32 s11, s10, 31
	s_lshl_b64 s[10:11], s[10:11], 2
	s_or_b64 s[34:35], s[10:11], s[6:7]
	s_mul_i32 s60, s35, 0x8100
	v_mov_b32_e32 v28, 0
	v_mov_b32_e32 v29, 0
	v_mov_b32_e32 v30, 0
	v_mov_b32_e32 v31, 0
	s_and_saveexec_b64 s[10:11], vcc
	s_cbranch_execz .LBB0_432
	v_mad_u64_u32 v[0:1], s[12:13], s34, v59, v[32:33]
	v_add_u32_e32 v1, s60, v1
	global_load_dwordx4 v[28:31], v[0:1], off nt
.LBB0_432:
	s_or_b64 exec, exec, s[10:11]
	s_lshl_b64 s[10:11], s[34:35], 3
	s_add_u32 s10, s33, s10
	s_addc_u32 s11, s44, s11
	v_mov_b32_e32 v16, 0
	global_load_dwordx2 v[56:57], v16, s[10:11]
	s_xor_b32 s10, s50, -2
	s_add_i32 s12, s10, s46
	s_add_i32 s13, s40, 1
	s_and_b64 s[10:11], s[8:9], exec
	s_cselect_b32 s10, s13, s12
	s_add_i32 s10, s10, s45
	s_ashr_i32 s11, s10, 31
	s_lshl_b64 s[10:11], s[10:11], 2
	s_or_b64 s[30:31], s[10:11], s[6:7]
	s_mul_i32 s59, s31, 0x8100
	v_mov_b32_e32 v24, 0
	v_mov_b32_e32 v25, 0
	v_mov_b32_e32 v26, 0
	v_mov_b32_e32 v27, 0
	s_and_saveexec_b64 s[10:11], vcc
	s_cbranch_execz .LBB0_434
	v_mad_u64_u32 v[0:1], s[12:13], s30, v59, v[32:33]
	v_add_u32_e32 v1, s59, v1
	global_load_dwordx4 v[24:27], v[0:1], off nt
.LBB0_434:
	s_or_b64 exec, exec, s[10:11]
	s_lshl_b64 s[10:11], s[30:31], 3
	s_add_u32 s10, s33, s10
	s_addc_u32 s11, s44, s11
	global_load_dwordx2 v[54:55], v16, s[10:11]
	s_xor_b32 s10, s50, -3
	s_add_i32 s12, s10, s46
	s_add_i32 s13, s40, 2
	s_and_b64 s[10:11], s[8:9], exec
	s_cselect_b32 s10, s13, s12
	s_add_i32 s10, s10, s45
	s_ashr_i32 s11, s10, 31
	s_lshl_b64 s[10:11], s[10:11], 2
	s_or_b64 s[20:21], s[10:11], s[6:7]
	s_mul_i32 s58, s21, 0x8100
	v_mov_b32_e32 v17, 0
	v_mov_b32_e32 v18, 0
	v_mov_b32_e32 v19, 0
	s_and_saveexec_b64 s[10:11], vcc
	s_cbranch_execz .LBB0_436
	v_mad_u64_u32 v[0:1], s[12:13], s20, v59, v[32:33]
	v_add_u32_e32 v1, s58, v1
	global_load_dwordx4 v[16:19], v[0:1], off nt
.LBB0_436:
	s_or_b64 exec, exec, s[10:11]
	s_lshl_b64 s[10:11], s[20:21], 3
	s_add_u32 s10, s33, s10
	s_addc_u32 s11, s44, s11
	v_mov_b32_e32 v8, 0
	global_load_dwordx2 v[52:53], v8, s[10:11]
	s_xor_b32 s10, s50, -4
	s_add_i32 s12, s10, s46
	s_add_i32 s13, s40, 3
	s_and_b64 s[10:11], s[8:9], exec
	s_cselect_b32 s10, s13, s12
	s_add_i32 s10, s10, s45
	s_ashr_i32 s11, s10, 31
	s_lshl_b64 s[10:11], s[10:11], 2
	s_or_b64 s[18:19], s[10:11], s[6:7]
	s_mul_i32 s55, s19, 0x8100
	v_mov_b32_e32 v20, 0
	v_mov_b32_e32 v21, 0
	v_mov_b32_e32 v22, 0
	v_mov_b32_e32 v23, 0
	s_and_saveexec_b64 s[10:11], vcc
	s_cbranch_execz .LBB0_438
	v_mad_u64_u32 v[0:1], s[12:13], s18, v59, v[32:33]
	v_add_u32_e32 v1, s55, v1
	global_load_dwordx4 v[20:23], v[0:1], off nt
.LBB0_438:
	s_or_b64 exec, exec, s[10:11]
	s_lshl_b64 s[10:11], s[18:19], 3
	s_add_u32 s10, s33, s10
	s_addc_u32 s11, s44, s11
	global_load_dwordx2 v[50:51], v8, s[10:11]
	s_xor_b32 s10, s50, -5
	s_add_i32 s12, s10, s46
	s_add_i32 s13, s40, 4
	s_and_b64 s[10:11], s[8:9], exec
	s_cselect_b32 s10, s13, s12
	s_add_i32 s10, s10, s45
	s_ashr_i32 s11, s10, 31
	s_lshl_b64 s[10:11], s[10:11], 2
	s_or_b64 s[16:17], s[10:11], s[6:7]
	s_mul_i32 s54, s17, 0x8100
	v_mov_b32_e32 v9, 0
	v_mov_b32_e32 v10, 0
	v_mov_b32_e32 v11, 0
	s_and_saveexec_b64 s[10:11], vcc
	s_cbranch_execz .LBB0_440
	v_mad_u64_u32 v[0:1], s[12:13], s16, v59, v[32:33]
	v_add_u32_e32 v1, s54, v1
	global_load_dwordx4 v[8:11], v[0:1], off nt
.LBB0_440:
	s_or_b64 exec, exec, s[10:11]
	s_lshl_b64 s[10:11], s[16:17], 3
	s_add_u32 s10, s33, s10
	s_addc_u32 s11, s44, s11
	v_mov_b32_e32 v0, 0
	global_load_dwordx2 v[48:49], v0, s[10:11]
	s_xor_b32 s10, s50, -6
	s_add_i32 s12, s10, s46
	s_add_i32 s13, s40, 5
	s_and_b64 s[10:11], s[8:9], exec
	s_cselect_b32 s10, s13, s12
	s_add_i32 s10, s10, s45
	s_ashr_i32 s11, s10, 31
	s_lshl_b64 s[10:11], s[10:11], 2
	s_or_b64 s[14:15], s[10:11], s[6:7]
	s_mul_i32 s53, s15, 0x8100
	v_mov_b32_e32 v12, 0
	v_mov_b32_e32 v13, 0
	v_mov_b32_e32 v14, 0
	v_mov_b32_e32 v15, 0
	s_and_saveexec_b64 s[10:11], vcc
	s_cbranch_execz .LBB0_442
	v_mad_u64_u32 v[2:3], s[12:13], s14, v59, v[32:33]
	v_add_u32_e32 v3, s53, v3
	global_load_dwordx4 v[12:15], v[2:3], off nt
.LBB0_442:
	s_or_b64 exec, exec, s[10:11]
	s_lshl_b64 s[10:11], s[14:15], 3
	s_add_u32 s10, s33, s10
	s_addc_u32 s11, s44, s11
	global_load_dwordx2 v[46:47], v0, s[10:11]
	s_xor_b32 s10, s50, -7
	s_add_i32 s12, s10, s46
	s_add_i32 s13, s40, 6
	s_and_b64 s[10:11], s[8:9], exec
	s_cselect_b32 s10, s13, s12
	s_add_i32 s10, s10, s45
	s_ashr_i32 s11, s10, 31
	s_lshl_b64 s[10:11], s[10:11], 2
	s_or_b64 s[12:13], s[10:11], s[6:7]
	s_mul_i32 s52, s13, 0x8100
	v_mov_b32_e32 v1, 0
	v_mov_b32_e32 v2, 0
	v_mov_b32_e32 v3, 0
	s_and_saveexec_b64 s[10:11], vcc
	s_cbranch_execz .LBB0_444
	v_mad_u64_u32 v[0:1], s[62:63], s12, v59, v[32:33]
	v_add_u32_e32 v1, s52, v1
	global_load_dwordx4 v[0:3], v[0:1], off nt
.LBB0_444:
	s_or_b64 exec, exec, s[10:11]
	s_lshl_b64 s[10:11], s[12:13], 3
	s_add_u32 s10, s33, s10
	s_addc_u32 s11, s44, s11
	v_mov_b32_e32 v4, 0
	global_load_dwordx2 v[36:37], v4, s[10:11]
	s_xor_b32 s10, s50, -8
	s_add_i32 s41, s10, s46
	s_add_i32 s40, s40, 7
	s_and_b64 s[10:11], s[8:9], exec
	s_cselect_b32 s10, s40, s41
	s_add_i32 s10, s10, s45
	s_ashr_i32 s11, s10, 31
	s_lshl_b64 s[10:11], s[10:11], 2
	s_or_b64 s[10:11], s[10:11], s[6:7]
	s_mul_i32 s51, s11, 0x8100
	v_mov_b32_e32 v5, 0
	v_mov_b32_e32 v6, 0
	v_mov_b32_e32 v7, 0
	s_and_saveexec_b64 s[40:41], vcc
	s_cbranch_execz .LBB0_446
	v_mad_u64_u32 v[4:5], s[62:63], s10, v59, v[32:33]
	v_add_u32_e32 v5, s51, v5
	global_load_dwordx4 v[4:7], v[4:5], off nt

; DI unsigned pk2(float lo, float hi) { const f32n2 v = {lo, hi}; return __builtin_bit_cast(unsigned, __builtin_convertvector(v, bf16n2)); }
; DI void scan_item(const Ctx& c, int st, int slice, int lane) {
;     ...
;         for (int u = 0; u < 8; ++u) { const int ch = d ? chunk0 + nch - 1 - (i0 + u) : chunk0 + i0 + u; const size_t ti = (size_t)(d * NCHUNK + ch) * 4 + head;
;             if (slice == 0 && lane == 0) MP[ti] = m;
;             u32x4 o; o.x = pk2(C[0], C[1]); o.y = pk2(C[2], C[3]); o.z = pk2(C[4], C[5]); o.w = pk2(C[6], C[7]);
;             if (act) *(u32x4*)(CST + ti * ST_ELEMS + e0) = o;
.LBB0_448:
	s_or_b64 exec, exec, s[40:41]
	s_and_saveexec_b64 s[40:41], s[0:1]
	s_xor_b64 s[40:41], exec, s[40:41]
	s_andn2_saveexec_b64 s[40:41], s[40:41]
	s_cbranch_execz .LBB0_450
	v_mad_u64_u32 v[66:67], s[34:35], s34, v59, v[32:33]
	v_cvt_pk_bf16_f32 v65, v44, v45
	v_cvt_pk_bf16_f32 v64, v42, v43
	v_cvt_pk_bf16_f32 v63, v40, v41
	v_cvt_pk_bf16_f32 v62, v38, v39
	v_add_u32_e32 v67, s60, v67
	global_store_dwordx4 v[66:67], v[62:65], off nt

; DI unsigned pk2(float lo, float hi) { const f32n2 v = {lo, hi}; return __builtin_bit_cast(unsigned, __builtin_convertvector(v, bf16n2)); }
; DI float bflo(unsigned w) { return __uint_as_float(w << 16); }
; DI float bfhi(unsigned w) { return __uint_as_float(w & 0xffff0000u); }
; DI void scan_item(const Ctx& c, int st, int slice, int lane) {
;     ...
;         for (int u = 0; u < 8; ++u) { const int ch = d ? chunk0 + nch - 1 - (i0 + u) : chunk0 + i0 + u; const size_t ti = (size_t)(d * NCHUNK + ch) * 4 + head;
;             if (slice == 0 && lane == 0) MP[ti] = m;
;             u32x4 o; o.x = pk2(C[0], C[1]); o.y = pk2(C[2], C[3]); o.z = pk2(C[4], C[5]); o.w = pk2(C[6], C[7]);
;             if (act) *(u32x4*)(CST + ti * ST_ELEMS + e0) = o;
;             const float mn = fmaxf(bt[u] + m, ml[u]), sp = __expf(bt[u] + m - mn), sl = __expf(ml[u] - mn); m = mn;
; #pragma unroll
;             for (int e = 0; e < 8; ++e) { const unsigned w = ld[u][e >> 1]; const float cl = (e & 1) ? bfhi(w) : bflo(w); C[e] = sp * C[e] + sl * cl; } }
.LBB0_452:
	s_or_b64 exec, exec, s[34:35]
	v_sub_f32_e32 v57, v57, v56
	v_sub_f32_e32 v60, v60, v56
	v_mul_f32_e32 v57, 0x3fb8aa3b, v57
	v_mul_f32_e32 v61, 0x3fb8aa3b, v60
	v_exp_f32_e32 v60, v57
	v_exp_f32_e32 v62, v61
	v_lshlrev_b32_e32 v64, 16, v28
	v_and_b32_e32 v65, 0xffff0000, v28
	v_lshlrev_b32_e32 v28, 16, v29
	v_and_b32_e32 v29, 0xffff0000, v29
	v_pk_mul_f32 v[28:29], v[60:61], v[28:29] op_sel_hi:[0,1]
	v_pk_fma_f32 v[28:29], v[40:41], v[62:63], v[28:29] op_sel_hi:[1,0,1]
	v_lshlrev_b32_e32 v40, 16, v30
	v_and_b32_e32 v41, 0xffff0000, v30
	v_lshlrev_b32_e32 v30, 16, v31
	v_and_b32_e32 v31, 0xffff0000, v31
	v_pk_mul_f32 v[64:65], v[60:61], v[64:65] op_sel_hi:[0,1]
	v_pk_mul_f32 v[40:41], v[60:61], v[40:41] op_sel_hi:[0,1]
	v_pk_mul_f32 v[30:31], v[60:61], v[30:31] op_sel_hi:[0,1]
	v_pk_fma_f32 v[38:39], v[38:39], v[62:63], v[64:65] op_sel_hi:[1,0,1]
	v_pk_fma_f32 v[40:41], v[42:43], v[62:63], v[40:41] op_sel_hi:[1,0,1]
	v_pk_fma_f32 v[30:31], v[44:45], v[62:63], v[30:31] op_sel_hi:[1,0,1]
	s_and_saveexec_b64 s[34:35], vcc
	s_cbranch_execz .LBB0_454
	v_mad_u64_u32 v[60:61], s[30:31], s30, v59, v[32:33]
	v_cvt_pk_bf16_f32 v45, v30, v31
	v_cvt_pk_bf16_f32 v44, v40, v41
	v_cvt_pk_bf16_f32 v43, v28, v29
	v_cvt_pk_bf16_f32 v42, v38, v39
	v_add_u32_e32 v61, s59, v61
	global_store_dwordx4 v[60:61], v[42:45], off nt

; DI unsigned pk2(float lo, float hi) { const f32n2 v = {lo, hi}; return __builtin_bit_cast(unsigned, __builtin_convertvector(v, bf16n2)); }
; DI float bflo(unsigned w) { return __uint_as_float(w << 16); }
; DI float bfhi(unsigned w) { return __uint_as_float(w & 0xffff0000u); }
; DI void scan_item(const Ctx& c, int st, int slice, int lane) {
;     ...
;         for (int u = 0; u < 8; ++u) { const int ch = d ? chunk0 + nch - 1 - (i0 + u) : chunk0 + i0 + u; const size_t ti = (size_t)(d * NCHUNK + ch) * 4 + head;
;             if (slice == 0 && lane == 0) MP[ti] = m;
;             u32x4 o; o.x = pk2(C[0], C[1]); o.y = pk2(C[2], C[3]); o.z = pk2(C[4], C[5]); o.w = pk2(C[6], C[7]);
;             if (act) *(u32x4*)(CST + ti * ST_ELEMS + e0) = o;
;             const float mn = fmaxf(bt[u] + m, ml[u]), sp = __expf(bt[u] + m - mn), sl = __expf(ml[u] - mn); m = mn;
; #pragma unroll
;             for (int e = 0; e < 8; ++e) { const unsigned w = ld[u][e >> 1]; const float cl = (e & 1) ? bfhi(w) : bflo(w); C[e] = sp * C[e] + sl * cl; } }
.LBB0_456:
	s_or_b64 exec, exec, s[30:31]
	v_sub_f32_e32 v44, v55, v42
	v_sub_f32_e32 v43, v43, v42
	v_mul_f32_e32 v44, 0x3fb8aa3b, v44
	v_mul_f32_e32 v43, 0x3fb8aa3b, v43
	v_exp_f32_e32 v44, v44
	v_exp_f32_e32 v54, v43
	v_lshlrev_b32_e32 v56, 16, v24
	v_and_b32_e32 v57, 0xffff0000, v24
	v_lshlrev_b32_e32 v24, 16, v25
	v_and_b32_e32 v25, 0xffff0000, v25
	v_pk_mul_f32 v[24:25], v[44:45], v[24:25] op_sel_hi:[0,1]
	v_pk_fma_f32 v[24:25], v[28:29], v[54:55], v[24:25] op_sel_hi:[1,0,1]
	v_lshlrev_b32_e32 v28, 16, v26
	v_and_b32_e32 v29, 0xffff0000, v26
	v_lshlrev_b32_e32 v26, 16, v27
	v_and_b32_e32 v27, 0xffff0000, v27
	v_pk_mul_f32 v[56:57], v[44:45], v[56:57] op_sel_hi:[0,1]
	v_pk_mul_f32 v[28:29], v[44:45], v[28:29] op_sel_hi:[0,1]
	v_pk_mul_f32 v[26:27], v[44:45], v[26:27] op_sel_hi:[0,1]
	v_pk_fma_f32 v[38:39], v[38:39], v[54:55], v[56:57] op_sel_hi:[1,0,1]
	v_pk_fma_f32 v[28:29], v[40:41], v[54:55], v[28:29] op_sel_hi:[1,0,1]
	v_pk_fma_f32 v[26:27], v[30:31], v[54:55], v[26:27] op_sel_hi:[1,0,1]
	s_and_saveexec_b64 s[30:31], vcc
	s_cbranch_execz .LBB0_458
	v_mad_u64_u32 v[30:31], s[20:21], s20, v59, v[32:33]
	v_cvt_pk_bf16_f32 v57, v26, v27
	v_cvt_pk_bf16_f32 v56, v28, v29
	v_cvt_pk_bf16_f32 v55, v24, v25
	v_cvt_pk_bf16_f32 v54, v38, v39
	v_add_u32_e32 v31, s58, v31
	global_store_dwordx4 v[30:31], v[54:57], off nt

; DI unsigned pk2(float lo, float hi) { const f32n2 v = {lo, hi}; return __builtin_bit_cast(unsigned, __builtin_convertvector(v, bf16n2)); }
; DI float bflo(unsigned w) { return __uint_as_float(w << 16); }
; DI float bfhi(unsigned w) { return __uint_as_float(w & 0xffff0000u); }
; DI void scan_item(const Ctx& c, int st, int slice, int lane) {
;     ...
;         for (int u = 0; u < 8; ++u) { const int ch = d ? chunk0 + nch - 1 - (i0 + u) : chunk0 + i0 + u; const size_t ti = (size_t)(d * NCHUNK + ch) * 4 + head;
;             if (slice == 0 && lane == 0) MP[ti] = m;
;             u32x4 o; o.x = pk2(C[0], C[1]); o.y = pk2(C[2], C[3]); o.z = pk2(C[4], C[5]); o.w = pk2(C[6], C[7]);
;             if (act) *(u32x4*)(CST + ti * ST_ELEMS + e0) = o;
;             const float mn = fmaxf(bt[u] + m, ml[u]), sp = __expf(bt[u] + m - mn), sl = __expf(ml[u] - mn); m = mn;
; #pragma unroll
;             for (int e = 0; e < 8; ++e) { const unsigned w = ld[u][e >> 1]; const float cl = (e & 1) ? bfhi(w) : bflo(w); C[e] = sp * C[e] + sl * cl; } }
.LBB0_460:
	s_or_b64 exec, exec, s[20:21]
	v_sub_f32_e32 v31, v53, v40
	v_sub_f32_e32 v30, v30, v40
	v_mul_f32_e32 v31, 0x3fb8aa3b, v31
	v_mul_f32_e32 v30, 0x3fb8aa3b, v30
	v_exp_f32_e32 v42, v31
	v_exp_f32_e32 v44, v30
	v_lshlrev_b32_e32 v30, 16, v16
	v_and_b32_e32 v31, 0xffff0000, v16
	v_lshlrev_b32_e32 v16, 16, v17
	v_and_b32_e32 v17, 0xffff0000, v17
	v_pk_mul_f32 v[16:17], v[42:43], v[16:17] op_sel_hi:[0,1]
	v_pk_fma_f32 v[16:17], v[24:25], v[44:45], v[16:17] op_sel_hi:[1,0,1]
	v_lshlrev_b32_e32 v24, 16, v18
	v_and_b32_e32 v25, 0xffff0000, v18
	v_lshlrev_b32_e32 v18, 16, v19
	v_and_b32_e32 v19, 0xffff0000, v19
	v_pk_mul_f32 v[30:31], v[42:43], v[30:31] op_sel_hi:[0,1]
	v_pk_mul_f32 v[24:25], v[42:43], v[24:25] op_sel_hi:[0,1]
	v_pk_mul_f32 v[18:19], v[42:43], v[18:19] op_sel_hi:[0,1]
	v_pk_fma_f32 v[30:31], v[38:39], v[44:45], v[30:31] op_sel_hi:[1,0,1]
	v_pk_fma_f32 v[24:25], v[28:29], v[44:45], v[24:25] op_sel_hi:[1,0,1]
	v_pk_fma_f32 v[18:19], v[26:27], v[44:45], v[18:19] op_sel_hi:[1,0,1]
	s_and_saveexec_b64 s[20:21], vcc
	s_cbranch_execz .LBB0_462
	v_mad_u64_u32 v[38:39], s[18:19], s18, v59, v[32:33]
	v_cvt_pk_bf16_f32 v29, v18, v19
	v_cvt_pk_bf16_f32 v28, v24, v25
	v_cvt_pk_bf16_f32 v27, v16, v17
	v_cvt_pk_bf16_f32 v26, v30, v31
	v_add_u32_e32 v39, s55, v39
	global_store_dwordx4 v[38:39], v[26:29], off nt

; DI unsigned pk2(float lo, float hi) { const f32n2 v = {lo, hi}; return __builtin_bit_cast(unsigned, __builtin_convertvector(v, bf16n2)); }
; DI float bflo(unsigned w) { return __uint_as_float(w << 16); }
; DI float bfhi(unsigned w) { return __uint_as_float(w & 0xffff0000u); }
; DI void scan_item(const Ctx& c, int st, int slice, int lane) {
;     ...
;         for (int u = 0; u < 8; ++u) { const int ch = d ? chunk0 + nch - 1 - (i0 + u) : chunk0 + i0 + u; const size_t ti = (size_t)(d * NCHUNK + ch) * 4 + head;
;             if (slice == 0 && lane == 0) MP[ti] = m;
;             u32x4 o; o.x = pk2(C[0], C[1]); o.y = pk2(C[2], C[3]); o.z = pk2(C[4], C[5]); o.w = pk2(C[6], C[7]);
;             if (act) *(u32x4*)(CST + ti * ST_ELEMS + e0) = o;
;             const float mn = fmaxf(bt[u] + m, ml[u]), sp = __expf(bt[u] + m - mn), sl = __expf(ml[u] - mn); m = mn;
; #pragma unroll
;             for (int e = 0; e < 8; ++e) { const unsigned w = ld[u][e >> 1]; const float cl = (e & 1) ? bfhi(w) : bflo(w); C[e] = sp * C[e] + sl * cl; } }
.LBB0_464:
	s_or_b64 exec, exec, s[18:19]
	v_sub_f32_e32 v27, v51, v28
	v_sub_f32_e32 v26, v26, v28
	v_mul_f32_e32 v27, 0x3fb8aa3b, v27
	v_mul_f32_e32 v26, 0x3fb8aa3b, v26
	v_exp_f32_e32 v38, v27
	v_exp_f32_e32 v40, v26
	v_lshlrev_b32_e32 v26, 16, v20
	v_and_b32_e32 v27, 0xffff0000, v20
	v_lshlrev_b32_e32 v20, 16, v21
	v_and_b32_e32 v21, 0xffff0000, v21
	v_pk_mul_f32 v[20:21], v[38:39], v[20:21] op_sel_hi:[0,1]
	v_pk_fma_f32 v[16:17], v[16:17], v[40:41], v[20:21] op_sel_hi:[1,0,1]
	v_lshlrev_b32_e32 v20, 16, v22
	v_and_b32_e32 v21, 0xffff0000, v22
	v_lshlrev_b32_e32 v22, 16, v23
	v_and_b32_e32 v23, 0xffff0000, v23
	v_pk_mul_f32 v[26:27], v[38:39], v[26:27] op_sel_hi:[0,1]
	v_pk_mul_f32 v[20:21], v[38:39], v[20:21] op_sel_hi:[0,1]
	v_pk_mul_f32 v[22:23], v[38:39], v[22:23] op_sel_hi:[0,1]
	v_pk_fma_f32 v[26:27], v[30:31], v[40:41], v[26:27] op_sel_hi:[1,0,1]
	v_pk_fma_f32 v[20:21], v[24:25], v[40:41], v[20:21] op_sel_hi:[1,0,1]
	v_pk_fma_f32 v[18:19], v[18:19], v[40:41], v[22:23] op_sel_hi:[1,0,1]
	s_and_saveexec_b64 s[18:19], vcc
	s_cbranch_execz .LBB0_466
	v_mad_u64_u32 v[30:31], s[16:17], s16, v59, v[32:33]
	v_cvt_pk_bf16_f32 v25, v18, v19
	v_cvt_pk_bf16_f32 v24, v20, v21
	v_cvt_pk_bf16_f32 v23, v16, v17
	v_cvt_pk_bf16_f32 v22, v26, v27
	v_add_u32_e32 v31, s54, v31
	global_store_dwordx4 v[30:31], v[22:25], off nt

; DI unsigned pk2(float lo, float hi) { const f32n2 v = {lo, hi}; return __builtin_bit_cast(unsigned, __builtin_convertvector(v, bf16n2)); }
; DI float bflo(unsigned w) { return __uint_as_float(w << 16); }
; DI float bfhi(unsigned w) { return __uint_as_float(w & 0xffff0000u); }
; DI void scan_item(const Ctx& c, int st, int slice, int lane) {
;     ...
;         for (int u = 0; u < 8; ++u) { const int ch = d ? chunk0 + nch - 1 - (i0 + u) : chunk0 + i0 + u; const size_t ti = (size_t)(d * NCHUNK + ch) * 4 + head;
;             if (slice == 0 && lane == 0) MP[ti] = m;
;             u32x4 o; o.x = pk2(C[0], C[1]); o.y = pk2(C[2], C[3]); o.z = pk2(C[4], C[5]); o.w = pk2(C[6], C[7]);
;             if (act) *(u32x4*)(CST + ti * ST_ELEMS + e0) = o;
;             const float mn = fmaxf(bt[u] + m, ml[u]), sp = __expf(bt[u] + m - mn), sl = __expf(ml[u] - mn); m = mn;
; #pragma unroll
;             for (int e = 0; e < 8; ++e) { const unsigned w = ld[u][e >> 1]; const float cl = (e & 1) ? bfhi(w) : bflo(w); C[e] = sp * C[e] + sl * cl; } }
.LBB0_468:
	s_or_b64 exec, exec, s[16:17]
	v_sub_f32_e32 v23, v49, v24
	v_sub_f32_e32 v22, v22, v24
	v_mul_f32_e32 v23, 0x3fb8aa3b, v23
	v_mul_f32_e32 v22, 0x3fb8aa3b, v22
	v_exp_f32_e32 v28, v23
	v_exp_f32_e32 v30, v22
	v_lshlrev_b32_e32 v22, 16, v8
	v_and_b32_e32 v23, 0xffff0000, v8
	v_lshlrev_b32_e32 v8, 16, v9
	v_and_b32_e32 v9, 0xffff0000, v9
	v_pk_mul_f32 v[8:9], v[28:29], v[8:9] op_sel_hi:[0,1]
	v_pk_fma_f32 v[8:9], v[16:17], v[30:31], v[8:9] op_sel_hi:[1,0,1]
	v_lshlrev_b32_e32 v16, 16, v10
	v_and_b32_e32 v17, 0xffff0000, v10
	v_lshlrev_b32_e32 v10, 16, v11
	v_and_b32_e32 v11, 0xffff0000, v11
	v_pk_mul_f32 v[22:23], v[28:29], v[22:23] op_sel_hi:[0,1]
	v_pk_mul_f32 v[16:17], v[28:29], v[16:17] op_sel_hi:[0,1]
	v_pk_mul_f32 v[10:11], v[28:29], v[10:11] op_sel_hi:[0,1]
	v_pk_fma_f32 v[22:23], v[26:27], v[30:31], v[22:23] op_sel_hi:[1,0,1]
	v_pk_fma_f32 v[16:17], v[20:21], v[30:31], v[16:17] op_sel_hi:[1,0,1]
	v_pk_fma_f32 v[10:11], v[18:19], v[30:31], v[10:11] op_sel_hi:[1,0,1]
	s_and_saveexec_b64 s[16:17], vcc
	s_cbranch_execz .LBB0_470
	v_mad_u64_u32 v[26:27], s[14:15], s14, v59, v[32:33]
	v_cvt_pk_bf16_f32 v21, v10, v11
	v_cvt_pk_bf16_f32 v20, v16, v17
	v_cvt_pk_bf16_f32 v19, v8, v9
	v_cvt_pk_bf16_f32 v18, v22, v23
	v_add_u32_e32 v27, s53, v27
	global_store_dwordx4 v[26:27], v[18:21], off nt

; DI unsigned pk2(float lo, float hi) { const f32n2 v = {lo, hi}; return __builtin_bit_cast(unsigned, __builtin_convertvector(v, bf16n2)); }
; DI float bflo(unsigned w) { return __uint_as_float(w << 16); }
; DI float bfhi(unsigned w) { return __uint_as_float(w & 0xffff0000u); }
; DI void scan_item(const Ctx& c, int st, int slice, int lane) {
;     ...
;         for (int u = 0; u < 8; ++u) { const int ch = d ? chunk0 + nch - 1 - (i0 + u) : chunk0 + i0 + u; const size_t ti = (size_t)(d * NCHUNK + ch) * 4 + head;
;             if (slice == 0 && lane == 0) MP[ti] = m;
;             u32x4 o; o.x = pk2(C[0], C[1]); o.y = pk2(C[2], C[3]); o.z = pk2(C[4], C[5]); o.w = pk2(C[6], C[7]);
;             if (act) *(u32x4*)(CST + ti * ST_ELEMS + e0) = o;
;             const float mn = fmaxf(bt[u] + m, ml[u]), sp = __expf(bt[u] + m - mn), sl = __expf(ml[u] - mn); m = mn;
; #pragma unroll
;             for (int e = 0; e < 8; ++e) { const unsigned w = ld[u][e >> 1]; const float cl = (e & 1) ? bfhi(w) : bflo(w); C[e] = sp * C[e] + sl * cl; } }
.LBB0_472:
	s_or_b64 exec, exec, s[14:15]
	v_sub_f32_e32 v19, v47, v20
	v_sub_f32_e32 v18, v18, v20
	v_mul_f32_e32 v19, 0x3fb8aa3b, v19
	v_mul_f32_e32 v18, 0x3fb8aa3b, v18
	v_exp_f32_e32 v24, v19
	v_exp_f32_e32 v26, v18
	v_lshlrev_b32_e32 v18, 16, v12
	v_and_b32_e32 v19, 0xffff0000, v12
	v_lshlrev_b32_e32 v12, 16, v13
	v_and_b32_e32 v13, 0xffff0000, v13
	v_pk_mul_f32 v[12:13], v[24:25], v[12:13] op_sel_hi:[0,1]
	v_pk_fma_f32 v[8:9], v[8:9], v[26:27], v[12:13] op_sel_hi:[1,0,1]
	v_lshlrev_b32_e32 v12, 16, v14
	v_and_b32_e32 v13, 0xffff0000, v14
	v_lshlrev_b32_e32 v14, 16, v15
	v_and_b32_e32 v15, 0xffff0000, v15
	v_pk_mul_f32 v[18:19], v[24:25], v[18:19] op_sel_hi:[0,1]
	v_pk_mul_f32 v[12:13], v[24:25], v[12:13] op_sel_hi:[0,1]
	v_pk_mul_f32 v[14:15], v[24:25], v[14:15] op_sel_hi:[0,1]
	v_pk_fma_f32 v[18:19], v[22:23], v[26:27], v[18:19] op_sel_hi:[1,0,1]
	v_pk_fma_f32 v[12:13], v[16:17], v[26:27], v[12:13] op_sel_hi:[1,0,1]
	v_pk_fma_f32 v[10:11], v[10:11], v[26:27], v[14:15] op_sel_hi:[1,0,1]
	s_and_saveexec_b64 s[14:15], vcc
	s_cbranch_execz .LBB0_474
	v_mad_u64_u32 v[22:23], s[12:13], s12, v59, v[32:33]
	v_cvt_pk_bf16_f32 v17, v10, v11
	v_cvt_pk_bf16_f32 v16, v12, v13
	v_cvt_pk_bf16_f32 v15, v8, v9
	v_cvt_pk_bf16_f32 v14, v18, v19
	v_add_u32_e32 v23, s52, v23
	global_store_dwordx4 v[22:23], v[14:17], off nt

; DI unsigned pk2(float lo, float hi) { const f32n2 v = {lo, hi}; return __builtin_bit_cast(unsigned, __builtin_convertvector(v, bf16n2)); }
; DI float bflo(unsigned w) { return __uint_as_float(w << 16); }
; DI float bfhi(unsigned w) { return __uint_as_float(w & 0xffff0000u); }
; DI void scan_item(const Ctx& c, int st, int slice, int lane) {
;     ...
;         for (int u = 0; u < 8; ++u) { const int ch = d ? chunk0 + nch - 1 - (i0 + u) : chunk0 + i0 + u; const size_t ti = (size_t)(d * NCHUNK + ch) * 4 + head;
;             if (slice == 0 && lane == 0) MP[ti] = m;
;             u32x4 o; o.x = pk2(C[0], C[1]); o.y = pk2(C[2], C[3]); o.z = pk2(C[4], C[5]); o.w = pk2(C[6], C[7]);
;             if (act) *(u32x4*)(CST + ti * ST_ELEMS + e0) = o;
;             const float mn = fmaxf(bt[u] + m, ml[u]), sp = __expf(bt[u] + m - mn), sl = __expf(ml[u] - mn); m = mn;
; #pragma unroll
;             for (int e = 0; e < 8; ++e) { const unsigned w = ld[u][e >> 1]; const float cl = (e & 1) ? bfhi(w) : bflo(w); C[e] = sp * C[e] + sl * cl; } }
.LBB0_476:
	s_or_b64 exec, exec, s[12:13]
	v_sub_f32_e32 v15, v37, v16
	v_sub_f32_e32 v14, v14, v16
	v_mul_f32_e32 v15, 0x3fb8aa3b, v15
	v_mul_f32_e32 v14, 0x3fb8aa3b, v14
	v_exp_f32_e32 v20, v15
	v_exp_f32_e32 v22, v14
	v_lshlrev_b32_e32 v14, 16, v0
	v_and_b32_e32 v15, 0xffff0000, v0
	v_lshlrev_b32_e32 v0, 16, v1
	v_and_b32_e32 v1, 0xffff0000, v1
	v_pk_mul_f32 v[0:1], v[20:21], v[0:1] op_sel_hi:[0,1]
	v_pk_fma_f32 v[8:9], v[8:9], v[22:23], v[0:1] op_sel_hi:[1,0,1]
	v_lshlrev_b32_e32 v0, 16, v2
	v_and_b32_e32 v1, 0xffff0000, v2
	v_pk_mul_f32 v[0:1], v[20:21], v[0:1] op_sel_hi:[0,1]
	v_pk_fma_f32 v[12:13], v[12:13], v[22:23], v[0:1] op_sel_hi:[1,0,1]
	v_lshlrev_b32_e32 v0, 16, v3
	v_and_b32_e32 v1, 0xffff0000, v3
	v_pk_mul_f32 v[14:15], v[20:21], v[14:15] op_sel_hi:[0,1]
	v_pk_mul_f32 v[0:1], v[20:21], v[0:1] op_sel_hi:[0,1]
	v_pk_fma_f32 v[14:15], v[18:19], v[22:23], v[14:15] op_sel_hi:[1,0,1]
	v_pk_fma_f32 v[0:1], v[10:11], v[22:23], v[0:1] op_sel_hi:[1,0,1]
	s_and_saveexec_b64 s[12:13], vcc
	s_cbranch_execz .LBB0_429
	v_mad_u64_u32 v[2:3], s[10:11], s10, v59, v[32:33]
	v_cvt_pk_bf16_f32 v21, v0, v1
	v_cvt_pk_bf16_f32 v20, v12, v13
	v_cvt_pk_bf16_f32 v19, v8, v9
	v_cvt_pk_bf16_f32 v18, v14, v15
	v_add_u32_e32 v3, s51, v3
	global_store_dwordx4 v[2:3], v[18:21], off nt
	s_branch .LBB0_429
